# early-MFMA: pre-MFMA s_barrier moved after the first 4 MFMAs of each phase in all 4 GEMM K-loops; P1/P5 epilogue loads hoisted
# baseline (speedup 1.0000x reference)
.LBB0_131:
	ds_read_b128 v[146:149], v157
	ds_read_b128 v[150:153], v157 offset:1024
	ds_read_b128 v[160:163], v157 offset:2048
	ds_read_b128 v[164:167], v157 offset:3072
	ds_read_b128 v[168:171], v158
	ds_read_b128 v[172:175], v158 offset:1024
	ds_read_b128 v[176:179], v158 offset:2048
	ds_read_b128 v[180:183], v158 offset:3072
	s_add_u32 s34, s30, 0xfff80080
	s_addc_u32 s35, s31, -1
	s_cmp_eq_u32 s55, 28
	s_cselect_b32 s37, s23, s35
	s_cselect_b32 s36, s51, s34
	s_cselect_b32 s35, s21, s54
	s_cselect_b32 s34, s52, s53
	v_lshl_add_u64 v[216:217], s[30:31], 0, v[138:139]
	s_add_i32 m0, s29, 0xc000
	ds_read_b128 v[184:187], v159
	ds_read_b128 v[188:191], v159 offset:1024
	ds_read_b128 v[192:195], v159 offset:2048
	ds_read_b128 v[196:199], v159 offset:3072
	ds_read_b128 v[200:203], v159 offset:4096
	ds_read_b128 v[204:207], v159 offset:5120
	ds_read_b128 v[208:211], v159 offset:6144
	ds_read_b128 v[212:215], v159 offset:7168
	global_load_lds_dwordx4 v[216:217], off
	v_lshl_add_u64 v[216:217], s[30:31], 0, v[140:141]
	s_add_i32 m0, s29, 0xe000
	s_nop 0
	global_load_lds_dwordx4 v[216:217], off
	s_waitcnt vmcnt(8)
	s_waitcnt lgkmcnt(0)
	s_setprio 1
	s_waitcnt lgkmcnt(0)
	v_mfma_f32_16x16x32_bf16 v[124:127], v[146:149], v[184:187], v[124:127]
	v_mfma_f32_16x16x32_bf16 v[120:123], v[160:163], v[184:187], v[120:123]
	v_mfma_f32_16x16x32_bf16 v[108:111], v[146:149], v[192:195], v[108:111]
	v_mfma_f32_16x16x32_bf16 v[104:107], v[160:163], v[192:195], v[104:107]
	s_barrier
	v_mfma_f32_16x16x32_bf16 v[92:95], v[146:149], v[200:203], v[92:95]
	v_mfma_f32_16x16x32_bf16 v[88:91], v[160:163], v[200:203], v[88:91]
	v_mfma_f32_16x16x32_bf16 v[76:79], v[146:149], v[208:211], v[76:79]
	v_mfma_f32_16x16x32_bf16 v[72:75], v[160:163], v[208:211], v[72:75]
	v_mfma_f32_16x16x32_bf16 v[124:127], v[150:153], v[188:191], v[124:127]
	v_mfma_f32_16x16x32_bf16 v[120:123], v[164:167], v[188:191], v[120:123]
	v_mfma_f32_16x16x32_bf16 v[108:111], v[150:153], v[196:199], v[108:111]
	v_mfma_f32_16x16x32_bf16 v[104:107], v[164:167], v[196:199], v[104:107]
	v_mfma_f32_16x16x32_bf16 v[92:95], v[150:153], v[204:207], v[92:95]
	v_mfma_f32_16x16x32_bf16 v[88:91], v[164:167], v[204:207], v[88:91]
	v_mfma_f32_16x16x32_bf16 v[76:79], v[150:153], v[212:215], v[76:79]
	v_mfma_f32_16x16x32_bf16 v[72:75], v[164:167], v[212:215], v[72:75]
	s_setprio 0
	s_setprio 1
	v_mfma_f32_16x16x32_bf16 v[116:119], v[168:171], v[184:187], v[116:119]
	v_mfma_f32_16x16x32_bf16 v[112:115], v[176:179], v[184:187], v[112:115]
	v_mfma_f32_16x16x32_bf16 v[100:103], v[168:171], v[192:195], v[100:103]
	v_mfma_f32_16x16x32_bf16 v[96:99], v[176:179], v[192:195], v[96:99]
	v_mfma_f32_16x16x32_bf16 v[84:87], v[168:171], v[200:203], v[84:87]
	v_mfma_f32_16x16x32_bf16 v[80:83], v[176:179], v[200:203], v[80:83]
	v_mfma_f32_16x16x32_bf16 v[68:71], v[168:171], v[208:211], v[68:71]
	v_mfma_f32_16x16x32_bf16 v[64:67], v[176:179], v[208:211], v[64:67]
	v_mfma_f32_16x16x32_bf16 v[116:119], v[172:175], v[188:191], v[116:119]
	v_mfma_f32_16x16x32_bf16 v[112:115], v[180:183], v[188:191], v[112:115]
	v_mfma_f32_16x16x32_bf16 v[100:103], v[172:175], v[196:199], v[100:103]
	v_mfma_f32_16x16x32_bf16 v[96:99], v[180:183], v[196:199], v[96:99]
	v_mfma_f32_16x16x32_bf16 v[84:87], v[172:175], v[204:207], v[84:87]
	v_mfma_f32_16x16x32_bf16 v[80:83], v[180:183], v[204:207], v[80:83]
	v_mfma_f32_16x16x32_bf16 v[68:71], v[172:175], v[212:215], v[68:71]
	v_mfma_f32_16x16x32_bf16 v[64:67], v[180:183], v[212:215], v[64:67]
	s_setprio 0
	s_barrier
	s_add_i32 s56, s47, s33
	v_lshl_add_u64 v[216:217], s[34:35], 0, v[134:135]
	s_mov_b32 m0, s56
	ds_read_b128 v[184:187], v159 offset:16384
	ds_read_b128 v[188:191], v159 offset:17408
	ds_read_b128 v[192:195], v159 offset:18432
	ds_read_b128 v[196:199], v159 offset:19456
	ds_read_b128 v[200:203], v159 offset:20480
	ds_read_b128 v[204:207], v159 offset:21504
	ds_read_b128 v[208:211], v159 offset:22528
	ds_read_b128 v[212:215], v159 offset:23552
	global_load_lds_dwordx4 v[216:217], off
	s_add_i32 m0, s56, 0x2000
	s_add_u32 s56, s34, 0x80000
	v_lshl_add_u64 v[218:219], s[34:35], 0, v[130:131]
	s_addc_u32 s57, s35, 0
	s_add_i32 s58, s48, s33
	global_load_lds_dwordx4 v[218:219], off
	v_lshl_add_u64 v[220:221], s[56:57], 0, v[134:135]
	s_mov_b32 m0, s58
	v_lshl_add_u64 v[222:223], s[36:37], 0, v[132:133]
	global_load_lds_dwordx4 v[220:221], off
	v_lshl_add_u64 v[220:221], s[56:57], 0, v[130:131]
	s_add_i32 m0, s58, 0x2000
	s_nop 0
	global_load_lds_dwordx4 v[220:221], off
	v_lshl_add_u64 v[220:221], s[36:37], 0, v[136:137]
	s_mov_b32 m0, s29
	s_nop 0
	global_load_lds_dwordx4 v[220:221], off
	s_mov_b32 m0, s40
	s_nop 0
	global_load_lds_dwordx4 v[222:223], off
	s_waitcnt vmcnt(8)
	s_waitcnt lgkmcnt(0)
	s_setprio 1
	s_waitcnt lgkmcnt(0)
	v_mfma_f32_16x16x32_bf16 v[60:63], v[146:149], v[184:187], v[60:63]
	v_mfma_f32_16x16x32_bf16 v[56:59], v[160:163], v[184:187], v[56:59]
	v_mfma_f32_16x16x32_bf16 v[44:47], v[146:149], v[192:195], v[44:47]
	v_mfma_f32_16x16x32_bf16 v[40:43], v[160:163], v[192:195], v[40:43]
	s_barrier
	v_mfma_f32_16x16x32_bf16 v[28:31], v[146:149], v[200:203], v[28:31]
	v_mfma_f32_16x16x32_bf16 v[24:27], v[160:163], v[200:203], v[24:27]
	v_mfma_f32_16x16x32_bf16 v[12:15], v[146:149], v[208:211], v[12:15]
	v_mfma_f32_16x16x32_bf16 v[8:11], v[160:163], v[208:211], v[8:11]
	v_mfma_f32_16x16x32_bf16 v[60:63], v[150:153], v[188:191], v[60:63]
	v_mfma_f32_16x16x32_bf16 v[56:59], v[164:167], v[188:191], v[56:59]
	v_mfma_f32_16x16x32_bf16 v[44:47], v[150:153], v[196:199], v[44:47]
	v_mfma_f32_16x16x32_bf16 v[40:43], v[164:167], v[196:199], v[40:43]
	v_mfma_f32_16x16x32_bf16 v[28:31], v[150:153], v[204:207], v[28:31]
	v_mfma_f32_16x16x32_bf16 v[24:27], v[164:167], v[204:207], v[24:27]
	v_mfma_f32_16x16x32_bf16 v[12:15], v[150:153], v[212:215], v[12:15]
	v_mfma_f32_16x16x32_bf16 v[8:11], v[164:167], v[212:215], v[8:11]
	s_setprio 0
	s_setprio 1
	v_mfma_f32_16x16x32_bf16 v[52:55], v[168:171], v[184:187], v[52:55]
	v_mfma_f32_16x16x32_bf16 v[48:51], v[176:179], v[184:187], v[48:51]
	v_mfma_f32_16x16x32_bf16 v[36:39], v[168:171], v[192:195], v[36:39]
	v_mfma_f32_16x16x32_bf16 v[32:35], v[176:179], v[192:195], v[32:35]
	v_mfma_f32_16x16x32_bf16 v[20:23], v[168:171], v[200:203], v[20:23]
	v_mfma_f32_16x16x32_bf16 v[16:19], v[176:179], v[200:203], v[16:19]
	v_mfma_f32_16x16x32_bf16 v[4:7], v[168:171], v[208:211], v[4:7]
	v_mfma_f32_16x16x32_bf16 v[0:3], v[176:179], v[208:211], v[0:3]
	v_mfma_f32_16x16x32_bf16 v[52:55], v[172:175], v[188:191], v[52:55]
	v_mfma_f32_16x16x32_bf16 v[48:51], v[180:183], v[188:191], v[48:51]
	v_mfma_f32_16x16x32_bf16 v[36:39], v[172:175], v[196:199], v[36:39]
	v_mfma_f32_16x16x32_bf16 v[32:35], v[180:183], v[196:199], v[32:35]
	v_mfma_f32_16x16x32_bf16 v[20:23], v[172:175], v[204:207], v[20:23]
	v_mfma_f32_16x16x32_bf16 v[16:19], v[180:183], v[204:207], v[16:19]
	v_mfma_f32_16x16x32_bf16 v[4:7], v[172:175], v[212:215], v[4:7]
	v_mfma_f32_16x16x32_bf16 v[0:3], v[180:183], v[212:215], v[0:3]
	s_setprio 0
	s_barrier
	s_add_i32 s56, 0, 0x18000
	s_add_i32 s57, 0, 0x1c000
	v_add_u32_e32 v164, s56, v155
	v_add_u32_e32 v180, s57, v155
	ds_read_b128 v[146:149], v164
	ds_read_b128 v[150:153], v164 offset:1024
	ds_read_b128 v[160:163], v164 offset:2048
	ds_read_b128 v[164:167], v164 offset:3072
	ds_read_b128 v[168:171], v180
	ds_read_b128 v[172:175], v180 offset:1024
	ds_read_b128 v[176:179], v180 offset:2048
	ds_read_b128 v[180:183], v180 offset:3072
	s_add_u32 s36, s36, 0x80000
	s_addc_u32 s37, s37, 0
	s_mov_b32 m0, s41
	v_lshl_add_u64 v[224:225], s[36:37], 0, v[136:137]
	ds_read_b128 v[184:187], v159 offset:32768
	ds_read_b128 v[188:191], v159 offset:33792
	ds_read_b128 v[192:195], v159 offset:34816
	ds_read_b128 v[196:199], v159 offset:35840
	ds_read_b128 v[200:203], v159 offset:36864
	ds_read_b128 v[204:207], v159 offset:37888
	ds_read_b128 v[208:211], v159 offset:38912
	ds_read_b128 v[212:215], v159 offset:39936
	global_load_lds_dwordx4 v[224:225], off
	v_lshl_add_u64 v[224:225], s[36:37], 0, v[132:133]
	s_mov_b32 m0, s42
	s_nop 0
	global_load_lds_dwordx4 v[224:225], off
	s_waitcnt vmcnt(8)
	s_waitcnt lgkmcnt(0)
	s_setprio 1
	s_waitcnt lgkmcnt(0)
	v_mfma_f32_16x16x32_bf16 v[124:127], v[146:149], v[184:187], v[124:127]
	v_mfma_f32_16x16x32_bf16 v[120:123], v[160:163], v[184:187], v[120:123]
	v_mfma_f32_16x16x32_bf16 v[108:111], v[146:149], v[192:195], v[108:111]
	v_mfma_f32_16x16x32_bf16 v[104:107], v[160:163], v[192:195], v[104:107]
	s_barrier
	v_mfma_f32_16x16x32_bf16 v[92:95], v[146:149], v[200:203], v[92:95]
	v_mfma_f32_16x16x32_bf16 v[88:91], v[160:163], v[200:203], v[88:91]
	v_mfma_f32_16x16x32_bf16 v[76:79], v[146:149], v[208:211], v[76:79]
	v_mfma_f32_16x16x32_bf16 v[72:75], v[160:163], v[208:211], v[72:75]
	v_mfma_f32_16x16x32_bf16 v[124:127], v[150:153], v[188:191], v[124:127]
	v_mfma_f32_16x16x32_bf16 v[120:123], v[164:167], v[188:191], v[120:123]
	v_mfma_f32_16x16x32_bf16 v[108:111], v[150:153], v[196:199], v[108:111]
	v_mfma_f32_16x16x32_bf16 v[104:107], v[164:167], v[196:199], v[104:107]
	v_mfma_f32_16x16x32_bf16 v[92:95], v[150:153], v[204:207], v[92:95]
	v_mfma_f32_16x16x32_bf16 v[88:91], v[164:167], v[204:207], v[88:91]
	v_mfma_f32_16x16x32_bf16 v[76:79], v[150:153], v[212:215], v[76:79]
	v_mfma_f32_16x16x32_bf16 v[72:75], v[164:167], v[212:215], v[72:75]
	s_setprio 0
	s_setprio 1
	v_mfma_f32_16x16x32_bf16 v[116:119], v[168:171], v[184:187], v[116:119]
	v_mfma_f32_16x16x32_bf16 v[112:115], v[176:179], v[184:187], v[112:115]
	v_mfma_f32_16x16x32_bf16 v[100:103], v[168:171], v[192:195], v[100:103]
	v_mfma_f32_16x16x32_bf16 v[96:99], v[176:179], v[192:195], v[96:99]
	v_mfma_f32_16x16x32_bf16 v[84:87], v[168:171], v[200:203], v[84:87]
	v_mfma_f32_16x16x32_bf16 v[80:83], v[176:179], v[200:203], v[80:83]
	v_mfma_f32_16x16x32_bf16 v[68:71], v[168:171], v[208:211], v[68:71]
	v_mfma_f32_16x16x32_bf16 v[64:67], v[176:179], v[208:211], v[64:67]
	v_mfma_f32_16x16x32_bf16 v[116:119], v[172:175], v[188:191], v[116:119]
	v_mfma_f32_16x16x32_bf16 v[112:115], v[180:183], v[188:191], v[112:115]
	v_mfma_f32_16x16x32_bf16 v[100:103], v[172:175], v[196:199], v[100:103]
	v_mfma_f32_16x16x32_bf16 v[96:99], v[180:183], v[196:199], v[96:99]
	v_mfma_f32_16x16x32_bf16 v[84:87], v[172:175], v[204:207], v[84:87]
	v_mfma_f32_16x16x32_bf16 v[80:83], v[180:183], v[204:207], v[80:83]
	v_mfma_f32_16x16x32_bf16 v[68:71], v[172:175], v[212:215], v[68:71]
	v_mfma_f32_16x16x32_bf16 v[64:67], v[180:183], v[212:215], v[64:67]
	s_setprio 0
	s_barrier
	s_add_i32 s36, s56, s33
	v_lshl_add_u64 v[216:217], v[216:217], 0, s[14:15]
	s_mov_b32 m0, s36
	ds_read_b128 v[184:187], v159 offset:49152
	ds_read_b128 v[188:191], v159 offset:50176
	ds_read_b128 v[192:195], v159 offset:51200
	ds_read_b128 v[196:199], v159 offset:52224
	ds_read_b128 v[200:203], v159 offset:53248
	ds_read_b128 v[204:207], v159 offset:54272
	ds_read_b128 v[208:211], v159 offset:55296
	ds_read_b128 v[212:215], v159 offset:56320
	global_load_lds_dwordx4 v[216:217], off
	s_add_i32 m0, s36, 0x2000
	s_add_u32 s34, s34, 0x80080
	v_lshl_add_u64 v[216:217], v[218:219], 0, s[14:15]
	s_addc_u32 s35, s35, 0
	s_add_i32 s36, s57, s33
	global_load_lds_dwordx4 v[216:217], off
	v_lshl_add_u64 v[216:217], s[34:35], 0, v[134:135]
	s_mov_b32 m0, s36
	s_nop 0
	global_load_lds_dwordx4 v[216:217], off
	v_lshl_add_u64 v[216:217], s[34:35], 0, v[130:131]
	s_add_i32 m0, s36, 0x2000
	s_nop 0
	global_load_lds_dwordx4 v[216:217], off
	v_lshl_add_u64 v[216:217], v[220:221], 0, s[14:15]
	s_mov_b32 m0, s44
	s_nop 0
	global_load_lds_dwordx4 v[216:217], off
	v_lshl_add_u64 v[216:217], v[222:223], 0, s[14:15]
	s_mov_b32 m0, s45
	s_nop 0
	global_load_lds_dwordx4 v[216:217], off
	s_waitcnt vmcnt(8)
	s_waitcnt lgkmcnt(0)
	s_setprio 1
	s_waitcnt lgkmcnt(0)
	v_mfma_f32_16x16x32_bf16 v[60:63], v[146:149], v[184:187], v[60:63]
	v_mfma_f32_16x16x32_bf16 v[56:59], v[160:163], v[184:187], v[56:59]
	v_mfma_f32_16x16x32_bf16 v[44:47], v[146:149], v[192:195], v[44:47]
	v_mfma_f32_16x16x32_bf16 v[40:43], v[160:163], v[192:195], v[40:43]
	s_barrier
	v_mfma_f32_16x16x32_bf16 v[28:31], v[146:149], v[200:203], v[28:31]
	v_mfma_f32_16x16x32_bf16 v[24:27], v[160:163], v[200:203], v[24:27]
	v_mfma_f32_16x16x32_bf16 v[12:15], v[146:149], v[208:211], v[12:15]
	v_mfma_f32_16x16x32_bf16 v[8:11], v[160:163], v[208:211], v[8:11]
	v_mfma_f32_16x16x32_bf16 v[60:63], v[150:153], v[188:191], v[60:63]
	v_mfma_f32_16x16x32_bf16 v[56:59], v[164:167], v[188:191], v[56:59]
	v_mfma_f32_16x16x32_bf16 v[44:47], v[150:153], v[196:199], v[44:47]
	v_mfma_f32_16x16x32_bf16 v[40:43], v[164:167], v[196:199], v[40:43]
	v_mfma_f32_16x16x32_bf16 v[28:31], v[150:153], v[204:207], v[28:31]
	v_mfma_f32_16x16x32_bf16 v[24:27], v[164:167], v[204:207], v[24:27]
	v_mfma_f32_16x16x32_bf16 v[12:15], v[150:153], v[212:215], v[12:15]
	v_mfma_f32_16x16x32_bf16 v[8:11], v[164:167], v[212:215], v[8:11]
	s_setprio 0
	s_setprio 1
	v_mfma_f32_16x16x32_bf16 v[52:55], v[168:171], v[184:187], v[52:55]
	v_mfma_f32_16x16x32_bf16 v[48:51], v[176:179], v[184:187], v[48:51]
	v_mfma_f32_16x16x32_bf16 v[36:39], v[168:171], v[192:195], v[36:39]
	v_mfma_f32_16x16x32_bf16 v[32:35], v[176:179], v[192:195], v[32:35]
	v_mfma_f32_16x16x32_bf16 v[20:23], v[168:171], v[200:203], v[20:23]
	v_mfma_f32_16x16x32_bf16 v[16:19], v[176:179], v[200:203], v[16:19]
	v_mfma_f32_16x16x32_bf16 v[4:7], v[168:171], v[208:211], v[4:7]
	v_mfma_f32_16x16x32_bf16 v[0:3], v[176:179], v[208:211], v[0:3]
	v_mfma_f32_16x16x32_bf16 v[52:55], v[172:175], v[188:191], v[52:55]
	v_mfma_f32_16x16x32_bf16 v[48:51], v[180:183], v[188:191], v[48:51]
	v_mfma_f32_16x16x32_bf16 v[36:39], v[172:175], v[196:199], v[36:39]
	v_mfma_f32_16x16x32_bf16 v[32:35], v[180:183], v[196:199], v[32:35]
	v_mfma_f32_16x16x32_bf16 v[20:23], v[172:175], v[204:207], v[20:23]
	v_mfma_f32_16x16x32_bf16 v[16:19], v[180:183], v[204:207], v[16:19]
	v_mfma_f32_16x16x32_bf16 v[4:7], v[172:175], v[212:215], v[4:7]
	v_mfma_f32_16x16x32_bf16 v[0:3], v[180:183], v[212:215], v[0:3]
	s_setprio 0
	s_barrier
	s_add_i32 s55, s55, 2
	s_add_u32 s30, s30, 0x100
	s_addc_u32 s31, s31, 0
	s_add_u32 s53, s53, 0x100
	s_addc_u32 s54, s54, 0
	s_cmp_gt_u32 s55, 29
	s_cbranch_scc0 .LBB0_131
	s_and_b64 vcc, exec, s[18:19]
	s_cbranch_vccz .LBB0_134
	s_barrier
.LBB0_134:
	v_lshl_add_u32 v146, s28, 8, v154
	v_ashrrev_i32_e32 v147, 31, v146
	v_lshl_add_u64 v[152:153], v[146:147], 2, s[92:93]
	global_load_dword v168, v[152:153], off
	global_load_dword v169, v[152:153], off offset:64
	global_load_dword v170, v[152:153], off offset:128
	global_load_dword v171, v[152:153], off offset:192
	global_load_dword v172, v[152:153], off offset:512
	global_load_dword v173, v[152:153], off offset:576
	global_load_dword v174, v[152:153], off offset:640
	global_load_dword v175, v[152:153], off offset:704
	v_lshl_or_b32 v150, s50, 8, v156
	v_mov_b64_e32 v[148:149], s[8:9]
	v_ashrrev_i32_e32 v151, 31, v150
	v_mad_i64_i32 v[162:163], s[30:31], v146, s49, v[148:149]
	v_lshlrev_b64 v[150:151], 1, v[150:151]
	v_lshl_add_u64 v[162:163], v[162:163], 0, v[150:151]
	s_andn2_b64 vcc, exec, s[0:1]
	s_mov_b64 s[0:1], -1
	s_waitcnt vmcnt(7)
	v_mov_b32_e32 v160, v168
	v_pk_mul_f32 v[126:127], v[126:127], v[160:161] op_sel_hi:[1,0]
	v_pk_mul_f32 v[124:125], v[124:125], v[160:161] op_sel_hi:[1,0]
	v_pk_mul_f32 v[122:123], v[122:123], v[160:161] op_sel_hi:[1,0]
	v_pk_mul_f32 v[120:121], v[120:121], v[160:161] op_sel_hi:[1,0]
	v_pk_mul_f32 v[118:119], v[118:119], v[160:161] op_sel_hi:[1,0]
	v_pk_mul_f32 v[116:117], v[116:117], v[160:161] op_sel_hi:[1,0]
	v_pk_mul_f32 v[164:165], v[114:115], v[160:161] op_sel_hi:[1,0]
	v_pk_mul_f32 v[160:161], v[112:113], v[160:161] op_sel_hi:[1,0]
	v_cvt_pk_bf16_f32 v112, v124, v125
	v_cvt_pk_bf16_f32 v113, v126, v127
	v_cvt_pk_bf16_f32 v114, v120, v121
	v_cvt_pk_bf16_f32 v115, v122, v123
	global_store_dwordx4 v[162:163], v[112:115], off
	s_nop 1
	v_cvt_pk_bf16_f32 v112, v116, v117
	v_cvt_pk_bf16_f32 v113, v118, v119
	v_cvt_pk_bf16_f32 v114, v160, v161
	v_cvt_pk_bf16_f32 v115, v164, v165
	global_store_dwordx4 v[162:163], v[112:115], off offset:256
	s_nop 0
	s_nop 0
	v_or_b32_e32 v113, 16, v146
	v_mad_i64_i32 v[114:115], s[30:31], v113, s49, v[148:149]
	v_lshl_add_u64 v[114:115], v[114:115], 0, v[150:151]
	s_waitcnt vmcnt(8)
	v_mov_b32_e32 v112, v169
	v_pk_mul_f32 v[110:111], v[110:111], v[112:113] op_sel_hi:[1,0]
	v_pk_mul_f32 v[108:109], v[108:109], v[112:113] op_sel_hi:[1,0]
	v_pk_mul_f32 v[106:107], v[106:107], v[112:113] op_sel_hi:[1,0]
	v_pk_mul_f32 v[104:105], v[104:105], v[112:113] op_sel_hi:[1,0]
	v_pk_mul_f32 v[102:103], v[102:103], v[112:113] op_sel_hi:[1,0]
	v_pk_mul_f32 v[100:101], v[100:101], v[112:113] op_sel_hi:[1,0]
	v_pk_mul_f32 v[116:117], v[98:99], v[112:113] op_sel_hi:[1,0]
	v_pk_mul_f32 v[112:113], v[96:97], v[112:113] op_sel_hi:[1,0]
	v_cvt_pk_bf16_f32 v96, v108, v109
	v_cvt_pk_bf16_f32 v97, v110, v111
	v_cvt_pk_bf16_f32 v98, v104, v105
	v_cvt_pk_bf16_f32 v99, v106, v107
	global_store_dwordx4 v[114:115], v[96:99], off
	s_nop 1
	v_cvt_pk_bf16_f32 v96, v100, v101
	v_cvt_pk_bf16_f32 v97, v102, v103
	v_cvt_pk_bf16_f32 v98, v112, v113
	v_cvt_pk_bf16_f32 v99, v116, v117
	global_store_dwordx4 v[114:115], v[96:99], off offset:256
	s_nop 0
	s_nop 0
	v_or_b32_e32 v97, 32, v146
	v_mad_i64_i32 v[98:99], s[30:31], v97, s49, v[148:149]
	v_lshl_add_u64 v[98:99], v[98:99], 0, v[150:151]
	s_waitcnt vmcnt(9)
	v_mov_b32_e32 v96, v170
	v_pk_mul_f32 v[94:95], v[94:95], v[96:97] op_sel_hi:[1,0]
	v_pk_mul_f32 v[92:93], v[92:93], v[96:97] op_sel_hi:[1,0]
	v_pk_mul_f32 v[90:91], v[90:91], v[96:97] op_sel_hi:[1,0]
	v_pk_mul_f32 v[88:89], v[88:89], v[96:97] op_sel_hi:[1,0]
	v_pk_mul_f32 v[86:87], v[86:87], v[96:97] op_sel_hi:[1,0]
	v_pk_mul_f32 v[84:85], v[84:85], v[96:97] op_sel_hi:[1,0]
	v_pk_mul_f32 v[100:101], v[82:83], v[96:97] op_sel_hi:[1,0]
	v_pk_mul_f32 v[96:97], v[80:81], v[96:97] op_sel_hi:[1,0]
	v_cvt_pk_bf16_f32 v80, v92, v93
	v_cvt_pk_bf16_f32 v81, v94, v95
	v_cvt_pk_bf16_f32 v82, v88, v89
	v_cvt_pk_bf16_f32 v83, v90, v91
	global_store_dwordx4 v[98:99], v[80:83], off
	s_nop 1
	v_cvt_pk_bf16_f32 v80, v84, v85
	v_cvt_pk_bf16_f32 v81, v86, v87
	v_cvt_pk_bf16_f32 v82, v96, v97
	v_cvt_pk_bf16_f32 v83, v100, v101
	global_store_dwordx4 v[98:99], v[80:83], off offset:256
	s_nop 0
	s_nop 0
	v_or_b32_e32 v81, 48, v146
	v_mad_i64_i32 v[82:83], s[30:31], v81, s49, v[148:149]
	v_lshl_add_u64 v[82:83], v[82:83], 0, v[150:151]
	s_waitcnt vmcnt(10)
	v_mov_b32_e32 v80, v171
	v_pk_mul_f32 v[78:79], v[78:79], v[80:81] op_sel_hi:[1,0]
	v_pk_mul_f32 v[76:77], v[76:77], v[80:81] op_sel_hi:[1,0]
	v_pk_mul_f32 v[74:75], v[74:75], v[80:81] op_sel_hi:[1,0]
	v_pk_mul_f32 v[72:73], v[72:73], v[80:81] op_sel_hi:[1,0]
	v_pk_mul_f32 v[70:71], v[70:71], v[80:81] op_sel_hi:[1,0]
	v_pk_mul_f32 v[68:69], v[68:69], v[80:81] op_sel_hi:[1,0]
	v_pk_mul_f32 v[84:85], v[66:67], v[80:81] op_sel_hi:[1,0]
	v_pk_mul_f32 v[80:81], v[64:65], v[80:81] op_sel_hi:[1,0]
	v_cvt_pk_bf16_f32 v64, v76, v77
	v_cvt_pk_bf16_f32 v65, v78, v79
	v_cvt_pk_bf16_f32 v66, v72, v73
	v_cvt_pk_bf16_f32 v67, v74, v75
	global_store_dwordx4 v[82:83], v[64:67], off
	s_nop 1
	v_cvt_pk_bf16_f32 v64, v68, v69
	v_cvt_pk_bf16_f32 v65, v70, v71
	v_cvt_pk_bf16_f32 v66, v80, v81
	v_cvt_pk_bf16_f32 v67, v84, v85
	global_store_dwordx4 v[82:83], v[64:67], off offset:256
	s_nop 0
	s_nop 0
	v_add_u32_e32 v65, 0x80, v146
	v_mad_i64_i32 v[66:67], s[30:31], v65, s49, v[148:149]
	v_lshl_add_u64 v[66:67], v[66:67], 0, v[150:151]
	s_waitcnt vmcnt(11)
	v_mov_b32_e32 v64, v172
	v_pk_mul_f32 v[62:63], v[62:63], v[64:65] op_sel_hi:[1,0]
	v_pk_mul_f32 v[60:61], v[60:61], v[64:65] op_sel_hi:[1,0]
	v_pk_mul_f32 v[58:59], v[58:59], v[64:65] op_sel_hi:[1,0]
	v_pk_mul_f32 v[56:57], v[56:57], v[64:65] op_sel_hi:[1,0]
	v_pk_mul_f32 v[54:55], v[54:55], v[64:65] op_sel_hi:[1,0]
	v_pk_mul_f32 v[52:53], v[52:53], v[64:65] op_sel_hi:[1,0]
	v_pk_mul_f32 v[68:69], v[50:51], v[64:65] op_sel_hi:[1,0]
	v_pk_mul_f32 v[64:65], v[48:49], v[64:65] op_sel_hi:[1,0]
	v_cvt_pk_bf16_f32 v48, v60, v61
	v_cvt_pk_bf16_f32 v49, v62, v63
	v_cvt_pk_bf16_f32 v50, v56, v57
	v_cvt_pk_bf16_f32 v51, v58, v59
	global_store_dwordx4 v[66:67], v[48:51], off
	s_nop 1
	v_cvt_pk_bf16_f32 v48, v52, v53
	v_cvt_pk_bf16_f32 v49, v54, v55
	v_cvt_pk_bf16_f32 v50, v64, v65
	v_cvt_pk_bf16_f32 v51, v68, v69
	global_store_dwordx4 v[66:67], v[48:51], off offset:256
	s_nop 0
	s_nop 0
	v_add_u32_e32 v49, 0x90, v146
	v_mad_i64_i32 v[50:51], s[30:31], v49, s49, v[148:149]
	v_lshl_add_u64 v[50:51], v[50:51], 0, v[150:151]
	s_waitcnt vmcnt(12)
	v_mov_b32_e32 v48, v173
	v_pk_mul_f32 v[46:47], v[46:47], v[48:49] op_sel_hi:[1,0]
	v_pk_mul_f32 v[44:45], v[44:45], v[48:49] op_sel_hi:[1,0]
	v_pk_mul_f32 v[42:43], v[42:43], v[48:49] op_sel_hi:[1,0]
	v_pk_mul_f32 v[40:41], v[40:41], v[48:49] op_sel_hi:[1,0]
	v_pk_mul_f32 v[38:39], v[38:39], v[48:49] op_sel_hi:[1,0]
	v_pk_mul_f32 v[36:37], v[36:37], v[48:49] op_sel_hi:[1,0]
	v_pk_mul_f32 v[52:53], v[34:35], v[48:49] op_sel_hi:[1,0]
	v_pk_mul_f32 v[48:49], v[32:33], v[48:49] op_sel_hi:[1,0]
	v_cvt_pk_bf16_f32 v32, v44, v45
	v_cvt_pk_bf16_f32 v33, v46, v47
	v_cvt_pk_bf16_f32 v34, v40, v41
	v_cvt_pk_bf16_f32 v35, v42, v43
	global_store_dwordx4 v[50:51], v[32:35], off
	s_nop 1
	v_cvt_pk_bf16_f32 v32, v36, v37
	v_cvt_pk_bf16_f32 v33, v38, v39
	v_cvt_pk_bf16_f32 v34, v48, v49
	v_cvt_pk_bf16_f32 v35, v52, v53
	global_store_dwordx4 v[50:51], v[32:35], off offset:256
	s_nop 0
	s_nop 0
	v_add_u32_e32 v33, 0xa0, v146
	v_mad_i64_i32 v[34:35], s[30:31], v33, s49, v[148:149]
	v_lshl_add_u64 v[34:35], v[34:35], 0, v[150:151]
	s_waitcnt vmcnt(13)
	v_mov_b32_e32 v32, v174
	v_pk_mul_f32 v[30:31], v[30:31], v[32:33] op_sel_hi:[1,0]
	v_pk_mul_f32 v[28:29], v[28:29], v[32:33] op_sel_hi:[1,0]
	v_pk_mul_f32 v[26:27], v[26:27], v[32:33] op_sel_hi:[1,0]
	v_pk_mul_f32 v[24:25], v[24:25], v[32:33] op_sel_hi:[1,0]
	v_pk_mul_f32 v[22:23], v[22:23], v[32:33] op_sel_hi:[1,0]
	v_pk_mul_f32 v[20:21], v[20:21], v[32:33] op_sel_hi:[1,0]
	v_pk_mul_f32 v[36:37], v[18:19], v[32:33] op_sel_hi:[1,0]
	v_pk_mul_f32 v[32:33], v[16:17], v[32:33] op_sel_hi:[1,0]
	v_cvt_pk_bf16_f32 v16, v28, v29
	v_cvt_pk_bf16_f32 v17, v30, v31
	v_cvt_pk_bf16_f32 v18, v24, v25
	v_cvt_pk_bf16_f32 v19, v26, v27
	global_store_dwordx4 v[34:35], v[16:19], off
	s_nop 1
	v_cvt_pk_bf16_f32 v16, v20, v21
	v_cvt_pk_bf16_f32 v17, v22, v23
	v_cvt_pk_bf16_f32 v18, v32, v33
	v_cvt_pk_bf16_f32 v19, v36, v37
	global_store_dwordx4 v[34:35], v[16:19], off offset:256
	s_nop 0
	s_nop 0
	v_add_u32_e32 v17, 0xb0, v146
	v_mad_i64_i32 v[18:19], s[30:31], v17, s49, v[148:149]
	v_lshl_add_u64 v[18:19], v[18:19], 0, v[150:151]
	s_waitcnt vmcnt(14)
	v_mov_b32_e32 v16, v175
	v_pk_mul_f32 v[14:15], v[14:15], v[16:17] op_sel_hi:[1,0]
	v_pk_mul_f32 v[12:13], v[12:13], v[16:17] op_sel_hi:[1,0]
	v_pk_mul_f32 v[10:11], v[10:11], v[16:17] op_sel_hi:[1,0]
	v_pk_mul_f32 v[8:9], v[8:9], v[16:17] op_sel_hi:[1,0]
	v_pk_mul_f32 v[6:7], v[6:7], v[16:17] op_sel_hi:[1,0]
	v_pk_mul_f32 v[4:5], v[4:5], v[16:17] op_sel_hi:[1,0]
	v_pk_mul_f32 v[20:21], v[2:3], v[16:17] op_sel_hi:[1,0]
	v_pk_mul_f32 v[16:17], v[0:1], v[16:17] op_sel_hi:[1,0]
	v_cvt_pk_bf16_f32 v0, v12, v13
	v_cvt_pk_bf16_f32 v1, v14, v15
	v_cvt_pk_bf16_f32 v2, v8, v9
	v_cvt_pk_bf16_f32 v3, v10, v11
	global_store_dwordx4 v[18:19], v[0:3], off
	s_nop 1
	v_cvt_pk_bf16_f32 v0, v4, v5
	v_cvt_pk_bf16_f32 v1, v6, v7
	v_cvt_pk_bf16_f32 v2, v16, v17
	v_cvt_pk_bf16_f32 v3, v20, v21
	global_store_dwordx4 v[18:19], v[0:3], off offset:256
	s_cbranch_vccnz .LBB0_127
	s_andn2_b64 vcc, exec, s[6:7]
	s_cbranch_vccnz .LBB0_126
	s_barrier
	s_branch .LBB0_126

.LBB0_585:
	v_add_u32_e32 v166, s42, v152
	v_add_u32_e32 v182, s43, v152
	s_add_u32 s26, s12, s24
	ds_read_b128 v[154:157], v166
	ds_read_b128 v[158:161], v166 offset:1024
	ds_read_b128 v[162:165], v166 offset:2048
	ds_read_b128 v[166:169], v166 offset:3072
	ds_read_b128 v[170:173], v182
	ds_read_b128 v[174:177], v182 offset:1024
	ds_read_b128 v[178:181], v182 offset:2048
	ds_read_b128 v[182:185], v182 offset:3072
	s_addc_u32 s27, s13, s25
	s_add_u32 s26, s26, 0x100
	s_addc_u32 s27, s27, 0
	s_add_u32 s50, s45, s24
	s_addc_u32 s51, s46, s25
	s_cmpk_eq_i32 s24, 0xf00
	s_cselect_b32 s29, s19, s27
	s_cselect_b32 s28, s47, s26
	s_cselect_b32 s27, s17, s51
	s_cselect_b32 s26, s48, s50
	v_lshl_add_u64 v[218:219], v[146:147], 0, s[24:25]
	s_add_i32 m0, s11, 0xc000
	ds_read_b128 v[186:189], v153
	ds_read_b128 v[190:193], v153 offset:1024
	ds_read_b128 v[194:197], v153 offset:2048
	ds_read_b128 v[198:201], v153 offset:3072
	ds_read_b128 v[202:205], v153 offset:4096
	ds_read_b128 v[206:209], v153 offset:5120
	ds_read_b128 v[210:213], v153 offset:6144
	ds_read_b128 v[214:217], v153 offset:7168
	global_load_lds_dwordx4 v[218:219], off
	v_lshl_add_u64 v[218:219], v[148:149], 0, s[24:25]
	s_add_i32 m0, s11, 0xe000
	s_nop 0
	global_load_lds_dwordx4 v[218:219], off
	s_waitcnt vmcnt(8)
	s_waitcnt lgkmcnt(0)
	s_setprio 1
	s_waitcnt lgkmcnt(0)
	v_mfma_f32_16x16x32_bf16 v[124:127], v[154:157], v[186:189], v[124:127]
	v_mfma_f32_16x16x32_bf16 v[120:123], v[162:165], v[186:189], v[120:123]
	v_mfma_f32_16x16x32_bf16 v[108:111], v[154:157], v[194:197], v[108:111]
	v_mfma_f32_16x16x32_bf16 v[104:107], v[162:165], v[194:197], v[104:107]
	s_barrier
	v_mfma_f32_16x16x32_bf16 v[92:95], v[154:157], v[202:205], v[92:95]
	v_mfma_f32_16x16x32_bf16 v[88:91], v[162:165], v[202:205], v[88:91]
	v_mfma_f32_16x16x32_bf16 v[76:79], v[154:157], v[210:213], v[76:79]
	v_mfma_f32_16x16x32_bf16 v[72:75], v[162:165], v[210:213], v[72:75]
	v_mfma_f32_16x16x32_bf16 v[124:127], v[158:161], v[190:193], v[124:127]
	v_mfma_f32_16x16x32_bf16 v[120:123], v[166:169], v[190:193], v[120:123]
	v_mfma_f32_16x16x32_bf16 v[108:111], v[158:161], v[198:201], v[108:111]
	v_mfma_f32_16x16x32_bf16 v[104:107], v[166:169], v[198:201], v[104:107]
	v_mfma_f32_16x16x32_bf16 v[92:95], v[158:161], v[206:209], v[92:95]
	v_mfma_f32_16x16x32_bf16 v[88:91], v[166:169], v[206:209], v[88:91]
	v_mfma_f32_16x16x32_bf16 v[76:79], v[158:161], v[214:217], v[76:79]
	v_mfma_f32_16x16x32_bf16 v[72:75], v[166:169], v[214:217], v[72:75]
	s_setprio 0
	s_setprio 1
	v_mfma_f32_16x16x32_bf16 v[116:119], v[170:173], v[186:189], v[116:119]
	v_mfma_f32_16x16x32_bf16 v[112:115], v[178:181], v[186:189], v[112:115]
	v_mfma_f32_16x16x32_bf16 v[100:103], v[170:173], v[194:197], v[100:103]
	v_mfma_f32_16x16x32_bf16 v[96:99], v[178:181], v[194:197], v[96:99]
	v_mfma_f32_16x16x32_bf16 v[84:87], v[170:173], v[202:205], v[84:87]
	v_mfma_f32_16x16x32_bf16 v[80:83], v[178:181], v[202:205], v[80:83]
	v_mfma_f32_16x16x32_bf16 v[68:71], v[170:173], v[210:213], v[68:71]
	v_mfma_f32_16x16x32_bf16 v[64:67], v[178:181], v[210:213], v[64:67]
	v_mfma_f32_16x16x32_bf16 v[116:119], v[174:177], v[190:193], v[116:119]
	v_mfma_f32_16x16x32_bf16 v[112:115], v[182:185], v[190:193], v[112:115]
	v_mfma_f32_16x16x32_bf16 v[100:103], v[174:177], v[198:201], v[100:103]
	v_mfma_f32_16x16x32_bf16 v[96:99], v[182:185], v[198:201], v[96:99]
	v_mfma_f32_16x16x32_bf16 v[84:87], v[174:177], v[206:209], v[84:87]
	v_mfma_f32_16x16x32_bf16 v[80:83], v[182:185], v[206:209], v[80:83]
	v_mfma_f32_16x16x32_bf16 v[68:71], v[174:177], v[214:217], v[68:71]
	v_mfma_f32_16x16x32_bf16 v[64:67], v[182:185], v[214:217], v[64:67]
	s_setprio 0
	s_barrier
	s_add_i32 s50, s42, s35
	v_lshl_add_u64 v[218:219], s[26:27], 0, v[132:133]
	s_mov_b32 m0, s50
	ds_read_b128 v[186:189], v153 offset:16384
	ds_read_b128 v[190:193], v153 offset:17408
	ds_read_b128 v[194:197], v153 offset:18432
	ds_read_b128 v[198:201], v153 offset:19456
	ds_read_b128 v[202:205], v153 offset:20480
	ds_read_b128 v[206:209], v153 offset:21504
	ds_read_b128 v[210:213], v153 offset:22528
	ds_read_b128 v[214:217], v153 offset:23552
	global_load_lds_dwordx4 v[218:219], off
	s_add_i32 m0, s50, 0x2000
	s_add_u32 s50, s26, 0x80000
	v_lshl_add_u64 v[220:221], s[26:27], 0, v[136:137]
	s_addc_u32 s51, s27, 0
	s_add_i32 s52, s43, s35
	global_load_lds_dwordx4 v[220:221], off
	v_lshl_add_u64 v[222:223], s[50:51], 0, v[132:133]
	s_mov_b32 m0, s52
	v_lshl_add_u64 v[224:225], s[28:29], 0, v[134:135]
	global_load_lds_dwordx4 v[222:223], off
	v_lshl_add_u64 v[222:223], s[50:51], 0, v[136:137]
	s_add_i32 m0, s52, 0x2000
	s_nop 0
	global_load_lds_dwordx4 v[222:223], off
	v_lshl_add_u64 v[222:223], s[28:29], 0, v[130:131]
	s_mov_b32 m0, s11
	s_nop 0
	global_load_lds_dwordx4 v[222:223], off
	s_mov_b32 m0, s36
	s_nop 0
	global_load_lds_dwordx4 v[224:225], off
	s_waitcnt vmcnt(8)
	s_waitcnt lgkmcnt(0)
	s_setprio 1
	s_waitcnt lgkmcnt(0)
	v_mfma_f32_16x16x32_bf16 v[60:63], v[154:157], v[186:189], v[60:63]
	v_mfma_f32_16x16x32_bf16 v[56:59], v[162:165], v[186:189], v[56:59]
	v_mfma_f32_16x16x32_bf16 v[44:47], v[154:157], v[194:197], v[44:47]
	v_mfma_f32_16x16x32_bf16 v[40:43], v[162:165], v[194:197], v[40:43]
	s_barrier
	v_mfma_f32_16x16x32_bf16 v[28:31], v[154:157], v[202:205], v[28:31]
	v_mfma_f32_16x16x32_bf16 v[24:27], v[162:165], v[202:205], v[24:27]
	v_mfma_f32_16x16x32_bf16 v[12:15], v[154:157], v[210:213], v[12:15]
	v_mfma_f32_16x16x32_bf16 v[8:11], v[162:165], v[210:213], v[8:11]
	v_mfma_f32_16x16x32_bf16 v[60:63], v[158:161], v[190:193], v[60:63]
	v_mfma_f32_16x16x32_bf16 v[56:59], v[166:169], v[190:193], v[56:59]
	v_mfma_f32_16x16x32_bf16 v[44:47], v[158:161], v[198:201], v[44:47]
	v_mfma_f32_16x16x32_bf16 v[40:43], v[166:169], v[198:201], v[40:43]
	v_mfma_f32_16x16x32_bf16 v[28:31], v[158:161], v[206:209], v[28:31]
	v_mfma_f32_16x16x32_bf16 v[24:27], v[166:169], v[206:209], v[24:27]
	v_mfma_f32_16x16x32_bf16 v[12:15], v[158:161], v[214:217], v[12:15]
	v_mfma_f32_16x16x32_bf16 v[8:11], v[166:169], v[214:217], v[8:11]
	s_setprio 0
	s_setprio 1
	v_mfma_f32_16x16x32_bf16 v[52:55], v[170:173], v[186:189], v[52:55]
	v_mfma_f32_16x16x32_bf16 v[48:51], v[178:181], v[186:189], v[48:51]
	v_mfma_f32_16x16x32_bf16 v[36:39], v[170:173], v[194:197], v[36:39]
	v_mfma_f32_16x16x32_bf16 v[32:35], v[178:181], v[194:197], v[32:35]
	v_mfma_f32_16x16x32_bf16 v[20:23], v[170:173], v[202:205], v[20:23]
	v_mfma_f32_16x16x32_bf16 v[16:19], v[178:181], v[202:205], v[16:19]
	v_mfma_f32_16x16x32_bf16 v[4:7], v[170:173], v[210:213], v[4:7]
	v_mfma_f32_16x16x32_bf16 v[0:3], v[178:181], v[210:213], v[0:3]
	v_mfma_f32_16x16x32_bf16 v[52:55], v[174:177], v[190:193], v[52:55]
	v_mfma_f32_16x16x32_bf16 v[48:51], v[182:185], v[190:193], v[48:51]
	v_mfma_f32_16x16x32_bf16 v[36:39], v[174:177], v[198:201], v[36:39]
	v_mfma_f32_16x16x32_bf16 v[32:35], v[182:185], v[198:201], v[32:35]
	v_mfma_f32_16x16x32_bf16 v[20:23], v[174:177], v[206:209], v[20:23]
	v_mfma_f32_16x16x32_bf16 v[16:19], v[182:185], v[206:209], v[16:19]
	v_mfma_f32_16x16x32_bf16 v[4:7], v[174:177], v[214:217], v[4:7]
	v_mfma_f32_16x16x32_bf16 v[0:3], v[182:185], v[214:217], v[0:3]
	s_setprio 0
	s_barrier
	s_add_i32 s50, 0, 0x18000
	s_add_i32 s51, 0, 0x1c000
	v_add_u32_e32 v166, s50, v152
	v_add_u32_e32 v182, s51, v152
	ds_read_b128 v[154:157], v166
	ds_read_b128 v[158:161], v166 offset:1024
	ds_read_b128 v[162:165], v166 offset:2048
	ds_read_b128 v[166:169], v166 offset:3072
	ds_read_b128 v[170:173], v182
	ds_read_b128 v[174:177], v182 offset:1024
	ds_read_b128 v[178:181], v182 offset:2048
	ds_read_b128 v[182:185], v182 offset:3072
	s_add_u32 s28, s28, 0x80000
	s_addc_u32 s29, s29, 0
	s_mov_b32 m0, s37
	v_lshl_add_u64 v[226:227], s[28:29], 0, v[130:131]
	ds_read_b128 v[186:189], v153 offset:32768
	ds_read_b128 v[190:193], v153 offset:33792
	ds_read_b128 v[194:197], v153 offset:34816
	ds_read_b128 v[198:201], v153 offset:35840
	ds_read_b128 v[202:205], v153 offset:36864
	ds_read_b128 v[206:209], v153 offset:37888
	ds_read_b128 v[210:213], v153 offset:38912
	ds_read_b128 v[214:217], v153 offset:39936
	global_load_lds_dwordx4 v[226:227], off
	v_lshl_add_u64 v[226:227], s[28:29], 0, v[134:135]
	s_mov_b32 m0, s38
	s_nop 0
	global_load_lds_dwordx4 v[226:227], off
	s_waitcnt vmcnt(8)
	s_waitcnt lgkmcnt(0)
	s_setprio 1
	s_waitcnt lgkmcnt(0)
	v_mfma_f32_16x16x32_bf16 v[124:127], v[154:157], v[186:189], v[124:127]
	v_mfma_f32_16x16x32_bf16 v[120:123], v[162:165], v[186:189], v[120:123]
	v_mfma_f32_16x16x32_bf16 v[108:111], v[154:157], v[194:197], v[108:111]
	v_mfma_f32_16x16x32_bf16 v[104:107], v[162:165], v[194:197], v[104:107]
	s_barrier
	v_mfma_f32_16x16x32_bf16 v[92:95], v[154:157], v[202:205], v[92:95]
	v_mfma_f32_16x16x32_bf16 v[88:91], v[162:165], v[202:205], v[88:91]
	v_mfma_f32_16x16x32_bf16 v[76:79], v[154:157], v[210:213], v[76:79]
	v_mfma_f32_16x16x32_bf16 v[72:75], v[162:165], v[210:213], v[72:75]
	v_mfma_f32_16x16x32_bf16 v[124:127], v[158:161], v[190:193], v[124:127]
	v_mfma_f32_16x16x32_bf16 v[120:123], v[166:169], v[190:193], v[120:123]
	v_mfma_f32_16x16x32_bf16 v[108:111], v[158:161], v[198:201], v[108:111]
	v_mfma_f32_16x16x32_bf16 v[104:107], v[166:169], v[198:201], v[104:107]
	v_mfma_f32_16x16x32_bf16 v[92:95], v[158:161], v[206:209], v[92:95]
	v_mfma_f32_16x16x32_bf16 v[88:91], v[166:169], v[206:209], v[88:91]
	v_mfma_f32_16x16x32_bf16 v[76:79], v[158:161], v[214:217], v[76:79]
	v_mfma_f32_16x16x32_bf16 v[72:75], v[166:169], v[214:217], v[72:75]
	s_setprio 0
	s_setprio 1
	v_mfma_f32_16x16x32_bf16 v[116:119], v[170:173], v[186:189], v[116:119]
	v_mfma_f32_16x16x32_bf16 v[112:115], v[178:181], v[186:189], v[112:115]
	v_mfma_f32_16x16x32_bf16 v[100:103], v[170:173], v[194:197], v[100:103]
	v_mfma_f32_16x16x32_bf16 v[96:99], v[178:181], v[194:197], v[96:99]
	v_mfma_f32_16x16x32_bf16 v[84:87], v[170:173], v[202:205], v[84:87]
	v_mfma_f32_16x16x32_bf16 v[80:83], v[178:181], v[202:205], v[80:83]
	v_mfma_f32_16x16x32_bf16 v[68:71], v[170:173], v[210:213], v[68:71]
	v_mfma_f32_16x16x32_bf16 v[64:67], v[178:181], v[210:213], v[64:67]
	v_mfma_f32_16x16x32_bf16 v[116:119], v[174:177], v[190:193], v[116:119]
	v_mfma_f32_16x16x32_bf16 v[112:115], v[182:185], v[190:193], v[112:115]
	v_mfma_f32_16x16x32_bf16 v[100:103], v[174:177], v[198:201], v[100:103]
	v_mfma_f32_16x16x32_bf16 v[96:99], v[182:185], v[198:201], v[96:99]
	v_mfma_f32_16x16x32_bf16 v[84:87], v[174:177], v[206:209], v[84:87]
	v_mfma_f32_16x16x32_bf16 v[80:83], v[182:185], v[206:209], v[80:83]
	v_mfma_f32_16x16x32_bf16 v[68:71], v[174:177], v[214:217], v[68:71]
	v_mfma_f32_16x16x32_bf16 v[64:67], v[182:185], v[214:217], v[64:67]
	s_setprio 0
	s_barrier
	s_add_i32 s28, s50, s35
	v_lshl_add_u64 v[218:219], v[218:219], 0, s[14:15]
	s_mov_b32 m0, s28
	ds_read_b128 v[186:189], v153 offset:49152
	ds_read_b128 v[190:193], v153 offset:50176
	ds_read_b128 v[194:197], v153 offset:51200
	ds_read_b128 v[198:201], v153 offset:52224
	ds_read_b128 v[202:205], v153 offset:53248
	ds_read_b128 v[206:209], v153 offset:54272
	ds_read_b128 v[210:213], v153 offset:55296
	ds_read_b128 v[214:217], v153 offset:56320
	global_load_lds_dwordx4 v[218:219], off
	s_add_i32 m0, s28, 0x2000
	s_add_u32 s26, s26, 0x80080
	v_lshl_add_u64 v[218:219], v[220:221], 0, s[14:15]
	s_addc_u32 s27, s27, 0
	s_add_i32 s28, s51, s35
	global_load_lds_dwordx4 v[218:219], off
	v_lshl_add_u64 v[218:219], s[26:27], 0, v[132:133]
	s_mov_b32 m0, s28
	s_nop 0
	global_load_lds_dwordx4 v[218:219], off
	v_lshl_add_u64 v[218:219], s[26:27], 0, v[136:137]
	s_add_i32 m0, s28, 0x2000
	s_nop 0
	global_load_lds_dwordx4 v[218:219], off
	v_lshl_add_u64 v[218:219], v[222:223], 0, s[14:15]
	s_mov_b32 m0, s39
	s_nop 0
	global_load_lds_dwordx4 v[218:219], off
	v_lshl_add_u64 v[218:219], v[224:225], 0, s[14:15]
	s_mov_b32 m0, s40
	s_nop 0
	global_load_lds_dwordx4 v[218:219], off
	s_waitcnt vmcnt(8)
	s_waitcnt lgkmcnt(0)
	s_setprio 1
	s_waitcnt lgkmcnt(0)
	v_mfma_f32_16x16x32_bf16 v[60:63], v[154:157], v[186:189], v[60:63]
	v_mfma_f32_16x16x32_bf16 v[56:59], v[162:165], v[186:189], v[56:59]
	v_mfma_f32_16x16x32_bf16 v[44:47], v[154:157], v[194:197], v[44:47]
	v_mfma_f32_16x16x32_bf16 v[40:43], v[162:165], v[194:197], v[40:43]
	s_barrier
	v_mfma_f32_16x16x32_bf16 v[28:31], v[154:157], v[202:205], v[28:31]
	v_mfma_f32_16x16x32_bf16 v[24:27], v[162:165], v[202:205], v[24:27]
	v_mfma_f32_16x16x32_bf16 v[12:15], v[154:157], v[210:213], v[12:15]
	v_mfma_f32_16x16x32_bf16 v[8:11], v[162:165], v[210:213], v[8:11]
	v_mfma_f32_16x16x32_bf16 v[60:63], v[158:161], v[190:193], v[60:63]
	v_mfma_f32_16x16x32_bf16 v[56:59], v[166:169], v[190:193], v[56:59]
	v_mfma_f32_16x16x32_bf16 v[44:47], v[158:161], v[198:201], v[44:47]
	v_mfma_f32_16x16x32_bf16 v[40:43], v[166:169], v[198:201], v[40:43]
	v_mfma_f32_16x16x32_bf16 v[28:31], v[158:161], v[206:209], v[28:31]
	v_mfma_f32_16x16x32_bf16 v[24:27], v[166:169], v[206:209], v[24:27]
	v_mfma_f32_16x16x32_bf16 v[12:15], v[158:161], v[214:217], v[12:15]
	v_mfma_f32_16x16x32_bf16 v[8:11], v[166:169], v[214:217], v[8:11]
	s_setprio 0
	s_setprio 1
	v_mfma_f32_16x16x32_bf16 v[52:55], v[170:173], v[186:189], v[52:55]
	v_mfma_f32_16x16x32_bf16 v[48:51], v[178:181], v[186:189], v[48:51]
	v_mfma_f32_16x16x32_bf16 v[36:39], v[170:173], v[194:197], v[36:39]
	v_mfma_f32_16x16x32_bf16 v[32:35], v[178:181], v[194:197], v[32:35]
	v_mfma_f32_16x16x32_bf16 v[20:23], v[170:173], v[202:205], v[20:23]
	v_mfma_f32_16x16x32_bf16 v[16:19], v[178:181], v[202:205], v[16:19]
	v_mfma_f32_16x16x32_bf16 v[4:7], v[170:173], v[210:213], v[4:7]
	v_mfma_f32_16x16x32_bf16 v[0:3], v[178:181], v[210:213], v[0:3]
	v_mfma_f32_16x16x32_bf16 v[52:55], v[174:177], v[190:193], v[52:55]
	v_mfma_f32_16x16x32_bf16 v[48:51], v[182:185], v[190:193], v[48:51]
	v_mfma_f32_16x16x32_bf16 v[36:39], v[174:177], v[198:201], v[36:39]
	v_mfma_f32_16x16x32_bf16 v[32:35], v[182:185], v[198:201], v[32:35]
	v_mfma_f32_16x16x32_bf16 v[20:23], v[174:177], v[206:209], v[20:23]
	v_mfma_f32_16x16x32_bf16 v[16:19], v[182:185], v[206:209], v[16:19]
	v_mfma_f32_16x16x32_bf16 v[4:7], v[174:177], v[214:217], v[4:7]
	v_mfma_f32_16x16x32_bf16 v[0:3], v[182:185], v[214:217], v[0:3]
	s_setprio 0
	s_barrier
	s_add_i32 s49, s49, 2
	s_add_u32 s24, s24, 0x100
	s_addc_u32 s25, s25, 0
	s_cmp_gt_u32 s49, 29
	s_cbranch_scc0 .LBB0_585
	s_add_u32 s24, s45, 0xffffff00
	s_addc_u32 s25, s46, -1
	s_andn2_b64 vcc, exec, s[4:5]
	s_cbranch_vccnz .LBB0_588
	v_mov_b32_e32 v0, 0
	s_mov_b32 s8, s16
	s_mov_b32 s10, s18
	s_mov_b64 s[12:13], s[22:23]
	s_mov_b32 s41, s44
	v_mov_b32_e32 v1, v0
	v_mov_b32_e32 v2, v0
	v_mov_b32_e32 v3, v0
	v_mov_b32_e32 v4, v0
	v_mov_b32_e32 v5, v0
	v_mov_b32_e32 v6, v0
	v_mov_b32_e32 v7, v0
	v_mov_b32_e32 v16, v0
	v_mov_b32_e32 v17, v0
	v_mov_b32_e32 v18, v0
	v_mov_b32_e32 v19, v0
	v_mov_b32_e32 v20, v0
	v_mov_b32_e32 v21, v0
	v_mov_b32_e32 v22, v0
	v_mov_b32_e32 v23, v0
	v_mov_b32_e32 v32, v0
	v_mov_b32_e32 v33, v0
	v_mov_b32_e32 v34, v0
	v_mov_b32_e32 v35, v0
	v_mov_b32_e32 v36, v0
	v_mov_b32_e32 v37, v0
	v_mov_b32_e32 v38, v0
	v_mov_b32_e32 v39, v0
	v_mov_b32_e32 v48, v0
	v_mov_b32_e32 v49, v0
	v_mov_b32_e32 v50, v0
	v_mov_b32_e32 v51, v0
	v_mov_b32_e32 v52, v0
	v_mov_b32_e32 v53, v0
	v_mov_b32_e32 v54, v0
	v_mov_b32_e32 v55, v0
	v_mov_b32_e32 v8, v0
	v_mov_b32_e32 v9, v0
	v_mov_b32_e32 v10, v0
	v_mov_b32_e32 v11, v0
	v_mov_b32_e32 v12, v0
	v_mov_b32_e32 v13, v0
	v_mov_b32_e32 v14, v0
	v_mov_b32_e32 v15, v0
	v_mov_b32_e32 v24, v0
	v_mov_b32_e32 v25, v0
	v_mov_b32_e32 v26, v0
	v_mov_b32_e32 v27, v0
	v_mov_b32_e32 v28, v0
	v_mov_b32_e32 v29, v0
	v_mov_b32_e32 v30, v0
	v_mov_b32_e32 v31, v0
	v_mov_b32_e32 v40, v0
	v_mov_b32_e32 v41, v0
	v_mov_b32_e32 v42, v0
	v_mov_b32_e32 v43, v0
	v_mov_b32_e32 v44, v0
	v_mov_b32_e32 v45, v0
	v_mov_b32_e32 v46, v0
	v_mov_b32_e32 v47, v0
	v_mov_b32_e32 v56, v0
	v_mov_b32_e32 v57, v0
	v_mov_b32_e32 v58, v0
	v_mov_b32_e32 v59, v0
	v_mov_b32_e32 v60, v0
	v_mov_b32_e32 v61, v0
	v_mov_b32_e32 v62, v0
	v_mov_b32_e32 v63, v0
	v_mov_b32_e32 v64, v0
	v_mov_b32_e32 v65, v0
	v_mov_b32_e32 v66, v0
	v_mov_b32_e32 v67, v0
	v_mov_b32_e32 v68, v0
	v_mov_b32_e32 v69, v0
	v_mov_b32_e32 v70, v0
	v_mov_b32_e32 v71, v0
	v_mov_b32_e32 v80, v0
	v_mov_b32_e32 v81, v0
	v_mov_b32_e32 v82, v0
	v_mov_b32_e32 v83, v0
	v_mov_b32_e32 v84, v0
	v_mov_b32_e32 v85, v0
	v_mov_b32_e32 v86, v0
	v_mov_b32_e32 v87, v0
	v_mov_b32_e32 v96, v0
	v_mov_b32_e32 v97, v0
	v_mov_b32_e32 v98, v0
	v_mov_b32_e32 v99, v0
	v_mov_b32_e32 v100, v0
	v_mov_b32_e32 v101, v0
	v_mov_b32_e32 v102, v0
	v_mov_b32_e32 v103, v0
	v_mov_b32_e32 v112, v0
	v_mov_b32_e32 v113, v0
	v_mov_b32_e32 v114, v0
	v_mov_b32_e32 v115, v0
	v_mov_b32_e32 v116, v0
	v_mov_b32_e32 v117, v0
	v_mov_b32_e32 v118, v0
	v_mov_b32_e32 v119, v0
	v_mov_b32_e32 v72, v0
	v_mov_b32_e32 v73, v0
	v_mov_b32_e32 v74, v0
	v_mov_b32_e32 v75, v0
	v_mov_b32_e32 v76, v0
	v_mov_b32_e32 v77, v0
	v_mov_b32_e32 v78, v0
	v_mov_b32_e32 v79, v0
	v_mov_b32_e32 v88, v0
	v_mov_b32_e32 v89, v0
	v_mov_b32_e32 v90, v0
	v_mov_b32_e32 v91, v0
	v_mov_b32_e32 v92, v0
	v_mov_b32_e32 v93, v0
	v_mov_b32_e32 v94, v0
	v_mov_b32_e32 v95, v0
	v_mov_b32_e32 v104, v0
	v_mov_b32_e32 v105, v0
	v_mov_b32_e32 v106, v0
	v_mov_b32_e32 v107, v0
	v_mov_b32_e32 v108, v0
	v_mov_b32_e32 v109, v0
	v_mov_b32_e32 v110, v0
	v_mov_b32_e32 v111, v0
	v_mov_b32_e32 v120, v0
	v_mov_b32_e32 v121, v0
	v_mov_b32_e32 v122, v0
	v_mov_b32_e32 v123, v0
	v_mov_b32_e32 v124, v0
	v_mov_b32_e32 v125, v0
	v_mov_b32_e32 v126, v0
	v_mov_b32_e32 v127, v0
	s_andn2_b64 vcc, exec, s[0:1]
	s_cbranch_vccnz .LBB0_589
	s_branch .LBB0_590

.LBB0_592:
	s_add_u32 s4, s92, 0x5200000
	s_addc_u32 s5, s93, 0
	s_lshl_b32 s0, s2, 5
	s_lshl_b32 s1, s8, 8
	s_lshl_b32 s9, s10, 8
	s_or_b32 s0, s1, s0
	v_add_u32_e32 v132, s9, v150
	v_and_or_b32 v130, v151, 24, s0
	v_ashrrev_i32_e32 v133, 31, v132
	v_ashrrev_i32_e32 v131, 31, v130
	v_lshlrev_b64 v[132:133], 11, v[132:133]
	v_lshl_add_u64 v[132:133], v[132:133], 0, v[130:131]
	v_lshlrev_b64 v[136:137], 1, v[132:133]
	v_lshl_add_u64 v[138:139], s[90:91], 0, v[136:137]
	s_barrier
	global_load_dwordx4 v[156:159], v[138:139], off nt
	global_load_dwordx4 v[160:163], v[138:139], off offset:256 nt
	s_add_u32 s12, s90, 0x10000
	s_addc_u32 s13, s91, 0
	global_load_dwordx4 v[164:167], v136, s[12:13] nt
	global_load_dwordx4 v[168:171], v136, s[12:13] offset:256 nt
	s_add_u32 s12, s90, 0x20000
	s_addc_u32 s13, s91, 0
	global_load_dwordx4 v[172:175], v136, s[12:13] nt
	global_load_dwordx4 v[176:179], v136, s[12:13] offset:256 nt
	s_add_u32 s12, s90, 0x30000
	s_addc_u32 s13, s91, 0
	global_load_dwordx4 v[180:183], v136, s[12:13] nt
	global_load_dwordx4 v[184:187], v136, s[12:13] offset:256 nt
	s_add_u32 s12, s90, 0x80000
	s_addc_u32 s13, s91, 0
	global_load_dwordx4 v[188:191], v136, s[12:13] nt
	global_load_dwordx4 v[192:195], v136, s[12:13] offset:256 nt
	s_add_u32 s12, s90, 0x90000
	s_addc_u32 s13, s91, 0
	global_load_dwordx4 v[196:199], v136, s[12:13] nt
	global_load_dwordx4 v[200:203], v136, s[12:13] offset:256 nt
	s_add_u32 s12, s90, 0xa0000
	s_addc_u32 s13, s91, 0
	global_load_dwordx4 v[204:207], v136, s[12:13] nt
	global_load_dwordx4 v[208:211], v136, s[12:13] offset:256 nt
	s_add_u32 s12, s90, 0xb0000
	s_addc_u32 s13, s91, 0
	global_load_dwordx4 v[212:215], v136, s[12:13] nt
	global_load_dwordx4 v[216:219], v136, s[12:13] offset:256 nt
	v_lshl_add_u64 v[136:137], s[4:5], 0, v[136:137]
	s_lshl_b32 s0, s2, 2
	s_add_i32 s2, s0, 0
	v_cmp_gt_u32_e32 vcc, 16, v128
	s_waitcnt vmcnt(15)
	v_mov_b64_e32 v[132:133], v[156:157]
	v_mov_b64_e32 v[134:135], v[158:159]
	v_lshlrev_b32_e32 v140, 16, v132
	v_and_b32_e32 v141, 0xffff0000, v132
	v_lshlrev_b32_e32 v132, 16, v133
	v_and_b32_e32 v133, 0xffff0000, v133
	v_lshlrev_b32_e32 v142, 16, v134
	v_and_b32_e32 v143, 0xffff0000, v134
	v_lshlrev_b32_e32 v134, 16, v135
	v_and_b32_e32 v135, 0xffff0000, v135
	v_pk_add_f32 v[126:127], v[126:127], v[132:133]
	v_pk_add_f32 v[132:133], v[124:125], v[140:141]
	v_pk_add_f32 v[134:135], v[122:123], v[134:135]
	v_pk_add_f32 v[140:141], v[120:121], v[142:143]
	v_cvt_pk_bf16_f32 v120, v132, v133
	v_cvt_pk_bf16_f32 v121, v126, v127
	v_mul_f32_e32 v133, v133, v133
	v_cvt_pk_bf16_f32 v122, v140, v141
	v_cvt_pk_bf16_f32 v123, v134, v135
	global_store_dwordx4 v[136:137], v[120:123], off
	s_nop 0
	v_mul_f32_e32 v126, v126, v126
	v_mul_f32_e32 v139, v140, v140
	v_fmac_f32_e32 v133, v132, v132
	v_fmac_f32_e32 v126, v127, v127
	v_mul_f32_e32 v134, v134, v134
	v_fmac_f32_e32 v139, v141, v141
	v_add_f32_e32 v126, v133, v126
	v_fmac_f32_e32 v134, v135, v135
	v_add_f32_e32 v126, v139, v126
	v_add_f32_e32 v134, v134, v126
	v_mbcnt_lo_u32_b32 v120, -1, 0
	v_mbcnt_hi_u32_b32 v121, -1, v120
	v_and_b32_e32 v138, 64, v121
	v_xor_b32_e32 v120, 16, v121
	v_add_u32_e32 v138, 64, v138
	v_cmp_lt_i32_e64 s[0:1], v120, v138
	s_waitcnt vmcnt(15)
	v_mov_b64_e32 v[122:123], v[160:161]
	v_mov_b64_e32 v[124:125], v[162:163]
	v_lshlrev_b32_e32 v126, 16, v122
	v_and_b32_e32 v127, 0xffff0000, v122
	v_lshlrev_b32_e32 v122, 16, v123
	v_and_b32_e32 v123, 0xffff0000, v123
	v_lshlrev_b32_e32 v132, 16, v124
	v_and_b32_e32 v133, 0xffff0000, v124
	v_lshlrev_b32_e32 v124, 16, v125
	v_and_b32_e32 v125, 0xffff0000, v125
	v_pk_add_f32 v[118:119], v[118:119], v[122:123]
	v_pk_add_f32 v[116:117], v[116:117], v[126:127]
	v_pk_add_f32 v[122:123], v[114:115], v[124:125]
	v_pk_add_f32 v[124:125], v[112:113], v[132:133]
	v_mul_f32_e32 v112, v117, v117
	v_mul_f32_e32 v113, v118, v118
	v_mul_f32_e32 v114, v124, v124
	v_fmac_f32_e32 v112, v116, v116
	v_fmac_f32_e32 v113, v119, v119
	v_mul_f32_e32 v115, v122, v122
	v_fmac_f32_e32 v114, v125, v125
	v_add_f32_e32 v112, v112, v113
	v_fmac_f32_e32 v115, v123, v123
	v_add_f32_e32 v112, v114, v112
	v_cndmask_b32_e64 v120, v121, v120, s[0:1]
	v_add_f32_e32 v112, v115, v112
	v_lshlrev_b32_e32 v120, 2, v120
	v_add_f32_e32 v112, v134, v112
	ds_bpermute_b32 v113, v120, v112
	v_xor_b32_e32 v114, 32, v121
	v_cmp_lt_i32_e64 s[0:1], v114, v138
	v_cvt_pk_bf16_f32 v116, v116, v117
	v_cvt_pk_bf16_f32 v117, v118, v119
	s_waitcnt lgkmcnt(0)
	v_add_f32_e32 v113, v112, v113
	v_cvt_pk_bf16_f32 v118, v124, v125
	v_cvt_pk_bf16_f32 v119, v122, v123
	v_cndmask_b32_e64 v114, v121, v114, s[0:1]
	v_lshlrev_b32_e32 v112, 2, v114
	ds_bpermute_b32 v114, v112, v113
	global_store_dwordx4 v[136:137], v[116:119], off offset:256
	s_and_saveexec_b64 s[0:1], vcc
	s_cbranch_execz .LBB0_594
	v_lshl_add_u32 v115, v150, 4, s2
	s_waitcnt lgkmcnt(0)
	v_add_f32_e32 v113, v113, v114
	ds_write_b32 v115, v113
.LBB0_594:
	s_or_b64 exec, exec, s[0:1]
	v_or_b32_e32 v113, 16, v150
	s_waitcnt lgkmcnt(0)
	v_add_u32_e32 v114, s9, v113
	v_ashrrev_i32_e32 v115, 31, v114
	v_lshlrev_b64 v[114:115], 11, v[114:115]
	v_lshl_add_u64 v[114:115], v[114:115], 0, v[130:131]
	v_lshlrev_b64 v[118:119], 1, v[114:115]
	v_lshl_add_u64 v[122:123], s[90:91], 0, v[118:119]
	s_nop 0
	v_lshl_add_u64 v[118:119], s[4:5], 0, v[118:119]
	s_waitcnt vmcnt(15)
	v_mov_b64_e32 v[114:115], v[164:165]
	v_mov_b64_e32 v[116:117], v[166:167]
	v_lshlrev_b32_e32 v124, 16, v114
	v_and_b32_e32 v125, 0xffff0000, v114
	v_lshlrev_b32_e32 v114, 16, v115
	v_and_b32_e32 v115, 0xffff0000, v115
	v_lshlrev_b32_e32 v126, 16, v116
	v_and_b32_e32 v127, 0xffff0000, v116
	v_lshlrev_b32_e32 v116, 16, v117
	v_and_b32_e32 v117, 0xffff0000, v117
	v_pk_add_f32 v[110:111], v[110:111], v[114:115]
	v_pk_add_f32 v[108:109], v[108:109], v[124:125]
	v_pk_add_f32 v[114:115], v[106:107], v[116:117]
	v_pk_add_f32 v[116:117], v[104:105], v[126:127]
	v_cvt_pk_bf16_f32 v104, v108, v109
	v_cvt_pk_bf16_f32 v105, v110, v111
	v_mul_f32_e32 v109, v109, v109
	v_cvt_pk_bf16_f32 v106, v116, v117
	v_cvt_pk_bf16_f32 v107, v114, v115
	global_store_dwordx4 v[118:119], v[104:107], off
	s_nop 0
	v_mul_f32_e32 v110, v110, v110
	v_mul_f32_e32 v116, v116, v116
	v_fmac_f32_e32 v109, v108, v108
	v_fmac_f32_e32 v110, v111, v111
	v_mul_f32_e32 v114, v114, v114
	v_fmac_f32_e32 v116, v117, v117
	v_add_f32_e32 v108, v109, v110
	v_fmac_f32_e32 v114, v115, v115
	v_add_f32_e32 v108, v116, v108
	v_add_f32_e32 v114, v114, v108
	s_waitcnt vmcnt(15)
	v_mov_b64_e32 v[104:105], v[168:169]
	v_mov_b64_e32 v[106:107], v[170:171]
	v_lshlrev_b32_e32 v108, 16, v104
	v_and_b32_e32 v109, 0xffff0000, v104
	v_lshlrev_b32_e32 v104, 16, v105
	v_and_b32_e32 v105, 0xffff0000, v105
	v_lshlrev_b32_e32 v110, 16, v106
	v_and_b32_e32 v111, 0xffff0000, v106
	v_lshlrev_b32_e32 v106, 16, v107
	v_and_b32_e32 v107, 0xffff0000, v107
	v_pk_add_f32 v[102:103], v[102:103], v[104:105]
	v_pk_add_f32 v[100:101], v[100:101], v[108:109]
	v_pk_add_f32 v[104:105], v[98:99], v[106:107]
	v_pk_add_f32 v[106:107], v[96:97], v[110:111]
	v_mul_f32_e32 v96, v101, v101
	v_mul_f32_e32 v97, v102, v102
	v_mul_f32_e32 v98, v106, v106
	v_fmac_f32_e32 v96, v100, v100
	v_fmac_f32_e32 v97, v103, v103
	v_mul_f32_e32 v99, v104, v104
	v_fmac_f32_e32 v98, v107, v107
	v_add_f32_e32 v96, v96, v97
	v_add_f32_e32 v96, v98, v96
	v_fmac_f32_e32 v99, v105, v105
	v_add_f32_e32 v96, v99, v96
	v_add_f32_e32 v96, v114, v96
	ds_bpermute_b32 v97, v120, v96
	v_cvt_pk_bf16_f32 v98, v100, v101
	v_cvt_pk_bf16_f32 v99, v102, v103
	v_cvt_pk_bf16_f32 v100, v106, v107
	v_cvt_pk_bf16_f32 v101, v104, v105
	s_waitcnt lgkmcnt(0)
	v_add_f32_e32 v96, v96, v97
	ds_bpermute_b32 v97, v112, v96
	global_store_dwordx4 v[118:119], v[98:101], off offset:256
	s_and_saveexec_b64 s[0:1], vcc
	s_cbranch_execz .LBB0_596
	v_lshl_add_u32 v98, v113, 4, s2
	s_waitcnt lgkmcnt(0)
	v_add_f32_e32 v96, v96, v97
	ds_write_b32 v98, v96
.LBB0_596:
	s_or_b64 exec, exec, s[0:1]
	v_or_b32_e32 v96, 32, v150
	v_add_u32_e32 v98, s9, v96
	v_ashrrev_i32_e32 v99, 31, v98
	v_lshlrev_b64 v[98:99], 11, v[98:99]
	v_lshl_add_u64 v[98:99], v[98:99], 0, v[130:131]
	v_lshlrev_b64 v[102:103], 1, v[98:99]
	v_lshl_add_u64 v[104:105], s[90:91], 0, v[102:103]
	s_nop 0
	v_lshl_add_u64 v[102:103], s[4:5], 0, v[102:103]
	s_waitcnt vmcnt(15)
	v_mov_b64_e32 v[98:99], v[172:173]
	v_mov_b64_e32 v[100:101], v[174:175]
	v_lshlrev_b32_e32 v106, 16, v98
	v_and_b32_e32 v107, 0xffff0000, v98
	v_lshlrev_b32_e32 v98, 16, v99
	v_and_b32_e32 v99, 0xffff0000, v99
	v_lshlrev_b32_e32 v108, 16, v100
	v_and_b32_e32 v109, 0xffff0000, v100
	v_lshlrev_b32_e32 v100, 16, v101
	v_and_b32_e32 v101, 0xffff0000, v101
	v_pk_add_f32 v[94:95], v[94:95], v[98:99]
	v_pk_add_f32 v[92:93], v[92:93], v[106:107]
	v_pk_add_f32 v[98:99], v[90:91], v[100:101]
	v_pk_add_f32 v[100:101], v[88:89], v[108:109]
	v_cvt_pk_bf16_f32 v88, v92, v93
	v_cvt_pk_bf16_f32 v89, v94, v95
	v_mul_f32_e32 v93, v93, v93
	v_cvt_pk_bf16_f32 v90, v100, v101
	v_cvt_pk_bf16_f32 v91, v98, v99
	global_store_dwordx4 v[102:103], v[88:91], off
	s_nop 0
	v_mul_f32_e32 v94, v94, v94
	s_waitcnt lgkmcnt(0)
	v_mul_f32_e32 v97, v100, v100
	v_fmac_f32_e32 v93, v92, v92
	v_fmac_f32_e32 v94, v95, v95
	v_mul_f32_e32 v98, v98, v98
	v_fmac_f32_e32 v97, v101, v101
	v_add_f32_e32 v92, v93, v94
	v_fmac_f32_e32 v98, v99, v99
	v_add_f32_e32 v92, v97, v92
	v_add_f32_e32 v97, v98, v92
	s_waitcnt vmcnt(15)
	v_mov_b64_e32 v[88:89], v[176:177]
	v_mov_b64_e32 v[90:91], v[178:179]
	v_lshlrev_b32_e32 v92, 16, v88
	v_and_b32_e32 v93, 0xffff0000, v88
	v_lshlrev_b32_e32 v88, 16, v89
	v_and_b32_e32 v89, 0xffff0000, v89
	v_lshlrev_b32_e32 v94, 16, v90
	v_and_b32_e32 v95, 0xffff0000, v90
	v_lshlrev_b32_e32 v90, 16, v91
	v_and_b32_e32 v91, 0xffff0000, v91
	v_pk_add_f32 v[86:87], v[86:87], v[88:89]
	v_pk_add_f32 v[84:85], v[84:85], v[92:93]
	v_pk_add_f32 v[88:89], v[82:83], v[90:91]
	v_pk_add_f32 v[90:91], v[80:81], v[94:95]
	v_mul_f32_e32 v80, v85, v85
	v_mul_f32_e32 v81, v86, v86
	v_mul_f32_e32 v82, v90, v90
	v_fmac_f32_e32 v80, v84, v84
	v_fmac_f32_e32 v81, v87, v87
	v_mul_f32_e32 v83, v88, v88
	v_fmac_f32_e32 v82, v91, v91
	v_add_f32_e32 v80, v80, v81
	v_add_f32_e32 v80, v82, v80
	v_fmac_f32_e32 v83, v89, v89
	v_add_f32_e32 v80, v83, v80
	v_add_f32_e32 v80, v97, v80
	ds_bpermute_b32 v81, v120, v80
	v_cvt_pk_bf16_f32 v82, v84, v85
	v_cvt_pk_bf16_f32 v83, v86, v87
	v_cvt_pk_bf16_f32 v84, v90, v91
	v_cvt_pk_bf16_f32 v85, v88, v89
	s_waitcnt lgkmcnt(0)
	v_add_f32_e32 v80, v80, v81
	ds_bpermute_b32 v81, v112, v80
	global_store_dwordx4 v[102:103], v[82:85], off offset:256
	s_and_saveexec_b64 s[0:1], vcc
	s_cbranch_execz .LBB0_598
	v_lshl_add_u32 v82, v96, 4, s2
	s_waitcnt lgkmcnt(0)
	v_add_f32_e32 v80, v80, v81
	ds_write_b32 v82, v80
.LBB0_598:
	s_or_b64 exec, exec, s[0:1]
	v_or_b32_e32 v80, 48, v150
	v_add_u32_e32 v82, s9, v80
	v_ashrrev_i32_e32 v83, 31, v82
	v_lshlrev_b64 v[82:83], 11, v[82:83]
	v_lshl_add_u64 v[82:83], v[82:83], 0, v[130:131]
	v_lshlrev_b64 v[86:87], 1, v[82:83]
	v_lshl_add_u64 v[88:89], s[90:91], 0, v[86:87]
	s_nop 0
	v_lshl_add_u64 v[86:87], s[4:5], 0, v[86:87]
	s_waitcnt vmcnt(15)
	v_mov_b64_e32 v[82:83], v[180:181]
	v_mov_b64_e32 v[84:85], v[182:183]
	v_lshlrev_b32_e32 v90, 16, v82
	v_and_b32_e32 v91, 0xffff0000, v82
	v_lshlrev_b32_e32 v82, 16, v83
	v_and_b32_e32 v83, 0xffff0000, v83
	v_lshlrev_b32_e32 v92, 16, v84
	v_and_b32_e32 v93, 0xffff0000, v84
	v_lshlrev_b32_e32 v84, 16, v85
	v_and_b32_e32 v85, 0xffff0000, v85
	v_pk_add_f32 v[78:79], v[78:79], v[82:83]
	v_pk_add_f32 v[76:77], v[76:77], v[90:91]
	v_pk_add_f32 v[82:83], v[74:75], v[84:85]
	v_pk_add_f32 v[84:85], v[72:73], v[92:93]
	v_cvt_pk_bf16_f32 v72, v76, v77
	v_cvt_pk_bf16_f32 v73, v78, v79
	v_mul_f32_e32 v77, v77, v77
	v_cvt_pk_bf16_f32 v74, v84, v85
	v_cvt_pk_bf16_f32 v75, v82, v83
	global_store_dwordx4 v[86:87], v[72:75], off
	s_nop 0
	v_mul_f32_e32 v78, v78, v78
	s_waitcnt lgkmcnt(0)
	v_mul_f32_e32 v81, v84, v84
	v_fmac_f32_e32 v77, v76, v76
	v_fmac_f32_e32 v78, v79, v79
	v_mul_f32_e32 v82, v82, v82
	v_fmac_f32_e32 v81, v85, v85
	v_add_f32_e32 v76, v77, v78
	v_fmac_f32_e32 v82, v83, v83
	v_add_f32_e32 v76, v81, v76
	v_add_f32_e32 v81, v82, v76
	s_waitcnt vmcnt(15)
	v_mov_b64_e32 v[72:73], v[184:185]
	v_mov_b64_e32 v[74:75], v[186:187]
	v_lshlrev_b32_e32 v76, 16, v72
	v_and_b32_e32 v77, 0xffff0000, v72
	v_lshlrev_b32_e32 v72, 16, v73
	v_and_b32_e32 v73, 0xffff0000, v73
	v_lshlrev_b32_e32 v78, 16, v74
	v_and_b32_e32 v79, 0xffff0000, v74
	v_lshlrev_b32_e32 v74, 16, v75
	v_and_b32_e32 v75, 0xffff0000, v75
	v_pk_add_f32 v[70:71], v[70:71], v[72:73]
	v_pk_add_f32 v[68:69], v[68:69], v[76:77]
	v_pk_add_f32 v[72:73], v[66:67], v[74:75]
	v_pk_add_f32 v[74:75], v[64:65], v[78:79]
	v_mul_f32_e32 v64, v69, v69
	v_mul_f32_e32 v65, v70, v70
	v_mul_f32_e32 v66, v74, v74
	v_fmac_f32_e32 v64, v68, v68
	v_fmac_f32_e32 v65, v71, v71
	v_mul_f32_e32 v67, v72, v72
	v_fmac_f32_e32 v66, v75, v75
	v_add_f32_e32 v64, v64, v65
	v_add_f32_e32 v64, v66, v64
	v_fmac_f32_e32 v67, v73, v73
	v_add_f32_e32 v64, v67, v64
	v_add_f32_e32 v64, v81, v64
	ds_bpermute_b32 v65, v120, v64
	v_cvt_pk_bf16_f32 v66, v68, v69
	v_cvt_pk_bf16_f32 v67, v70, v71
	v_cvt_pk_bf16_f32 v68, v74, v75
	v_cvt_pk_bf16_f32 v69, v72, v73
	s_waitcnt lgkmcnt(0)
	v_add_f32_e32 v64, v64, v65
	ds_bpermute_b32 v65, v112, v64
	global_store_dwordx4 v[86:87], v[66:69], off offset:256
	s_and_saveexec_b64 s[0:1], vcc
	s_cbranch_execz .LBB0_600
	v_lshl_add_u32 v66, v80, 4, s2
	s_waitcnt lgkmcnt(0)
	v_add_f32_e32 v64, v64, v65
	ds_write_b32 v66, v64
.LBB0_600:
	s_or_b64 exec, exec, s[0:1]
	v_add_u32_e32 v64, 0x80, v150
	v_add_u32_e32 v66, s9, v64
	v_ashrrev_i32_e32 v67, 31, v66
	v_lshlrev_b64 v[66:67], 11, v[66:67]
	v_lshl_add_u64 v[66:67], v[66:67], 0, v[130:131]
	v_lshlrev_b64 v[70:71], 1, v[66:67]
	v_lshl_add_u64 v[72:73], s[90:91], 0, v[70:71]
	s_nop 0
	v_lshl_add_u64 v[70:71], s[4:5], 0, v[70:71]
	s_waitcnt vmcnt(15)
	v_mov_b64_e32 v[66:67], v[188:189]
	v_mov_b64_e32 v[68:69], v[190:191]
	v_lshlrev_b32_e32 v74, 16, v66
	v_and_b32_e32 v75, 0xffff0000, v66
	v_lshlrev_b32_e32 v66, 16, v67
	v_and_b32_e32 v67, 0xffff0000, v67
	v_lshlrev_b32_e32 v76, 16, v68
	v_and_b32_e32 v77, 0xffff0000, v68
	v_lshlrev_b32_e32 v68, 16, v69
	v_and_b32_e32 v69, 0xffff0000, v69
	v_pk_add_f32 v[62:63], v[62:63], v[66:67]
	v_pk_add_f32 v[60:61], v[60:61], v[74:75]
	v_pk_add_f32 v[66:67], v[58:59], v[68:69]
	v_pk_add_f32 v[68:69], v[56:57], v[76:77]
	v_cvt_pk_bf16_f32 v56, v60, v61
	v_cvt_pk_bf16_f32 v57, v62, v63
	v_mul_f32_e32 v61, v61, v61
	v_cvt_pk_bf16_f32 v58, v68, v69
	v_cvt_pk_bf16_f32 v59, v66, v67
	global_store_dwordx4 v[70:71], v[56:59], off
	s_nop 0
	v_mul_f32_e32 v62, v62, v62
	s_waitcnt lgkmcnt(0)
	v_mul_f32_e32 v65, v68, v68
	v_fmac_f32_e32 v61, v60, v60
	v_fmac_f32_e32 v62, v63, v63
	v_mul_f32_e32 v66, v66, v66
	v_fmac_f32_e32 v65, v69, v69
	v_add_f32_e32 v60, v61, v62
	v_fmac_f32_e32 v66, v67, v67
	v_add_f32_e32 v60, v65, v60
	v_add_f32_e32 v65, v66, v60
	s_waitcnt vmcnt(15)
	v_mov_b64_e32 v[56:57], v[192:193]
	v_mov_b64_e32 v[58:59], v[194:195]
	v_lshlrev_b32_e32 v60, 16, v56
	v_and_b32_e32 v61, 0xffff0000, v56
	v_lshlrev_b32_e32 v56, 16, v57
	v_and_b32_e32 v57, 0xffff0000, v57
	v_lshlrev_b32_e32 v62, 16, v58
	v_and_b32_e32 v63, 0xffff0000, v58
	v_lshlrev_b32_e32 v58, 16, v59
	v_and_b32_e32 v59, 0xffff0000, v59
	v_pk_add_f32 v[54:55], v[54:55], v[56:57]
	v_pk_add_f32 v[52:53], v[52:53], v[60:61]
	v_pk_add_f32 v[56:57], v[50:51], v[58:59]
	v_pk_add_f32 v[58:59], v[48:49], v[62:63]
	v_mul_f32_e32 v48, v53, v53
	v_mul_f32_e32 v49, v54, v54
	v_mul_f32_e32 v50, v58, v58
	v_fmac_f32_e32 v48, v52, v52
	v_fmac_f32_e32 v49, v55, v55
	v_mul_f32_e32 v51, v56, v56
	v_fmac_f32_e32 v50, v59, v59
	v_add_f32_e32 v48, v48, v49
	v_add_f32_e32 v48, v50, v48
	v_fmac_f32_e32 v51, v57, v57
	v_add_f32_e32 v48, v51, v48
	v_add_f32_e32 v48, v65, v48
	ds_bpermute_b32 v49, v120, v48
	v_cvt_pk_bf16_f32 v50, v52, v53
	v_cvt_pk_bf16_f32 v51, v54, v55
	v_cvt_pk_bf16_f32 v52, v58, v59
	v_cvt_pk_bf16_f32 v53, v56, v57
	s_waitcnt lgkmcnt(0)
	v_add_f32_e32 v48, v48, v49
	ds_bpermute_b32 v49, v112, v48
	global_store_dwordx4 v[70:71], v[50:53], off offset:256
	s_and_saveexec_b64 s[0:1], vcc
	s_cbranch_execz .LBB0_602
	v_lshl_add_u32 v50, v64, 4, s2
	s_waitcnt lgkmcnt(0)
	v_add_f32_e32 v48, v48, v49
	ds_write_b32 v50, v48
.LBB0_602:
	s_or_b64 exec, exec, s[0:1]
	v_add_u32_e32 v48, 0x90, v150
	v_add_u32_e32 v50, s9, v48
	v_ashrrev_i32_e32 v51, 31, v50
	v_lshlrev_b64 v[50:51], 11, v[50:51]
	v_lshl_add_u64 v[50:51], v[50:51], 0, v[130:131]
	v_lshlrev_b64 v[54:55], 1, v[50:51]
	v_lshl_add_u64 v[56:57], s[90:91], 0, v[54:55]
	s_nop 0
	v_lshl_add_u64 v[54:55], s[4:5], 0, v[54:55]
	s_waitcnt vmcnt(15)
	v_mov_b64_e32 v[50:51], v[196:197]
	v_mov_b64_e32 v[52:53], v[198:199]
	v_lshlrev_b32_e32 v58, 16, v50
	v_and_b32_e32 v59, 0xffff0000, v50
	v_lshlrev_b32_e32 v50, 16, v51
	v_and_b32_e32 v51, 0xffff0000, v51
	v_lshlrev_b32_e32 v60, 16, v52
	v_and_b32_e32 v61, 0xffff0000, v52
	v_lshlrev_b32_e32 v52, 16, v53
	v_and_b32_e32 v53, 0xffff0000, v53
	v_pk_add_f32 v[46:47], v[46:47], v[50:51]
	v_pk_add_f32 v[44:45], v[44:45], v[58:59]
	v_pk_add_f32 v[50:51], v[42:43], v[52:53]
	v_pk_add_f32 v[52:53], v[40:41], v[60:61]
	v_cvt_pk_bf16_f32 v40, v44, v45
	v_cvt_pk_bf16_f32 v41, v46, v47
	v_mul_f32_e32 v45, v45, v45
	v_cvt_pk_bf16_f32 v42, v52, v53
	v_cvt_pk_bf16_f32 v43, v50, v51
	global_store_dwordx4 v[54:55], v[40:43], off
	s_nop 0
	v_mul_f32_e32 v46, v46, v46
	s_waitcnt lgkmcnt(0)
	v_mul_f32_e32 v49, v52, v52
	v_fmac_f32_e32 v45, v44, v44
	v_fmac_f32_e32 v46, v47, v47
	v_mul_f32_e32 v50, v50, v50
	v_fmac_f32_e32 v49, v53, v53
	v_add_f32_e32 v44, v45, v46
	v_fmac_f32_e32 v50, v51, v51
	v_add_f32_e32 v44, v49, v44
	v_add_f32_e32 v49, v50, v44
	s_waitcnt vmcnt(15)
	v_mov_b64_e32 v[40:41], v[200:201]
	v_mov_b64_e32 v[42:43], v[202:203]
	v_lshlrev_b32_e32 v44, 16, v40
	v_and_b32_e32 v45, 0xffff0000, v40
	v_lshlrev_b32_e32 v40, 16, v41
	v_and_b32_e32 v41, 0xffff0000, v41
	v_lshlrev_b32_e32 v46, 16, v42
	v_and_b32_e32 v47, 0xffff0000, v42
	v_lshlrev_b32_e32 v42, 16, v43
	v_and_b32_e32 v43, 0xffff0000, v43
	v_pk_add_f32 v[38:39], v[38:39], v[40:41]
	v_pk_add_f32 v[36:37], v[36:37], v[44:45]
	v_pk_add_f32 v[40:41], v[34:35], v[42:43]
	v_pk_add_f32 v[42:43], v[32:33], v[46:47]
	v_mul_f32_e32 v32, v37, v37
	v_mul_f32_e32 v33, v38, v38
	v_mul_f32_e32 v34, v42, v42
	v_fmac_f32_e32 v32, v36, v36
	v_fmac_f32_e32 v33, v39, v39
	v_mul_f32_e32 v35, v40, v40
	v_fmac_f32_e32 v34, v43, v43
	v_add_f32_e32 v32, v32, v33
	v_add_f32_e32 v32, v34, v32
	v_fmac_f32_e32 v35, v41, v41
	v_add_f32_e32 v32, v35, v32
	v_add_f32_e32 v32, v49, v32
	ds_bpermute_b32 v33, v120, v32
	v_cvt_pk_bf16_f32 v34, v36, v37
	v_cvt_pk_bf16_f32 v35, v38, v39
	v_cvt_pk_bf16_f32 v36, v42, v43
	v_cvt_pk_bf16_f32 v37, v40, v41
	s_waitcnt lgkmcnt(0)
	v_add_f32_e32 v32, v32, v33
	ds_bpermute_b32 v33, v112, v32
	global_store_dwordx4 v[54:55], v[34:37], off offset:256
	s_and_saveexec_b64 s[0:1], vcc
	s_cbranch_execz .LBB0_604
	v_lshl_add_u32 v34, v48, 4, s2
	s_waitcnt lgkmcnt(0)
	v_add_f32_e32 v32, v32, v33
	ds_write_b32 v34, v32
.LBB0_604:
	s_or_b64 exec, exec, s[0:1]
	v_add_u32_e32 v32, 0xa0, v150
	v_add_u32_e32 v34, s9, v32
	v_ashrrev_i32_e32 v35, 31, v34
	v_lshlrev_b64 v[34:35], 11, v[34:35]
	v_lshl_add_u64 v[34:35], v[34:35], 0, v[130:131]
	v_lshlrev_b64 v[38:39], 1, v[34:35]
	v_lshl_add_u64 v[40:41], s[90:91], 0, v[38:39]
	s_nop 0
	v_lshl_add_u64 v[38:39], s[4:5], 0, v[38:39]
	s_waitcnt vmcnt(15)
	v_mov_b64_e32 v[34:35], v[204:205]
	v_mov_b64_e32 v[36:37], v[206:207]
	v_lshlrev_b32_e32 v42, 16, v34
	v_and_b32_e32 v43, 0xffff0000, v34
	v_lshlrev_b32_e32 v34, 16, v35
	v_and_b32_e32 v35, 0xffff0000, v35
	v_lshlrev_b32_e32 v44, 16, v36
	v_and_b32_e32 v45, 0xffff0000, v36
	v_lshlrev_b32_e32 v36, 16, v37
	v_and_b32_e32 v37, 0xffff0000, v37
	v_pk_add_f32 v[30:31], v[30:31], v[34:35]
	v_pk_add_f32 v[28:29], v[28:29], v[42:43]
	v_pk_add_f32 v[34:35], v[26:27], v[36:37]
	v_pk_add_f32 v[36:37], v[24:25], v[44:45]
	v_cvt_pk_bf16_f32 v24, v28, v29
	v_cvt_pk_bf16_f32 v25, v30, v31
	v_mul_f32_e32 v29, v29, v29
	v_cvt_pk_bf16_f32 v26, v36, v37
	v_cvt_pk_bf16_f32 v27, v34, v35
	global_store_dwordx4 v[38:39], v[24:27], off
	s_nop 0
	v_mul_f32_e32 v30, v30, v30
	s_waitcnt lgkmcnt(0)
	v_mul_f32_e32 v33, v36, v36
	v_fmac_f32_e32 v29, v28, v28
	v_fmac_f32_e32 v30, v31, v31
	v_mul_f32_e32 v34, v34, v34
	v_fmac_f32_e32 v33, v37, v37
	v_add_f32_e32 v28, v29, v30
	v_fmac_f32_e32 v34, v35, v35
	v_add_f32_e32 v28, v33, v28
	v_add_f32_e32 v33, v34, v28
	s_waitcnt vmcnt(15)
	v_mov_b64_e32 v[24:25], v[208:209]
	v_mov_b64_e32 v[26:27], v[210:211]
	v_lshlrev_b32_e32 v28, 16, v24
	v_and_b32_e32 v29, 0xffff0000, v24
	v_lshlrev_b32_e32 v24, 16, v25
	v_and_b32_e32 v25, 0xffff0000, v25
	v_lshlrev_b32_e32 v30, 16, v26
	v_and_b32_e32 v31, 0xffff0000, v26
	v_lshlrev_b32_e32 v26, 16, v27
	v_and_b32_e32 v27, 0xffff0000, v27
	v_pk_add_f32 v[22:23], v[22:23], v[24:25]
	v_pk_add_f32 v[20:21], v[20:21], v[28:29]
	v_pk_add_f32 v[24:25], v[18:19], v[26:27]
	v_pk_add_f32 v[26:27], v[16:17], v[30:31]
	v_mul_f32_e32 v16, v21, v21
	v_mul_f32_e32 v17, v22, v22
	v_mul_f32_e32 v18, v26, v26
	v_fmac_f32_e32 v16, v20, v20
	v_fmac_f32_e32 v17, v23, v23
	v_mul_f32_e32 v19, v24, v24
	v_fmac_f32_e32 v18, v27, v27
	v_add_f32_e32 v16, v16, v17
	v_add_f32_e32 v16, v18, v16
	v_fmac_f32_e32 v19, v25, v25
	v_add_f32_e32 v16, v19, v16
	v_add_f32_e32 v16, v33, v16
	ds_bpermute_b32 v17, v120, v16
	v_cvt_pk_bf16_f32 v18, v20, v21
	v_cvt_pk_bf16_f32 v19, v22, v23
	v_cvt_pk_bf16_f32 v20, v26, v27
	v_cvt_pk_bf16_f32 v21, v24, v25
	s_waitcnt lgkmcnt(0)
	v_add_f32_e32 v16, v16, v17
	ds_bpermute_b32 v17, v112, v16
	global_store_dwordx4 v[38:39], v[18:21], off offset:256
	s_and_saveexec_b64 s[0:1], vcc
	s_cbranch_execz .LBB0_606
	v_lshl_add_u32 v18, v32, 4, s2
	s_waitcnt lgkmcnt(0)
	v_add_f32_e32 v16, v16, v17
	ds_write_b32 v18, v16
.LBB0_606:
	s_or_b64 exec, exec, s[0:1]
	v_add_u32_e32 v16, 0xb0, v150
	v_add_u32_e32 v18, s9, v16
	v_ashrrev_i32_e32 v19, 31, v18
	v_lshlrev_b64 v[18:19], 11, v[18:19]
	v_lshl_add_u64 v[18:19], v[18:19], 0, v[130:131]
	v_lshlrev_b64 v[22:23], 1, v[18:19]
	v_lshl_add_u64 v[24:25], s[90:91], 0, v[22:23]
	s_nop 0
	v_lshl_add_u64 v[22:23], s[4:5], 0, v[22:23]
	s_waitcnt vmcnt(15)
	v_mov_b64_e32 v[18:19], v[212:213]
	v_mov_b64_e32 v[20:21], v[214:215]
	v_lshlrev_b32_e32 v26, 16, v18
	v_and_b32_e32 v27, 0xffff0000, v18
	v_lshlrev_b32_e32 v18, 16, v19
	v_and_b32_e32 v19, 0xffff0000, v19
	v_lshlrev_b32_e32 v28, 16, v20
	v_and_b32_e32 v29, 0xffff0000, v20
	v_lshlrev_b32_e32 v20, 16, v21
	v_and_b32_e32 v21, 0xffff0000, v21
	v_pk_add_f32 v[14:15], v[14:15], v[18:19]
	v_pk_add_f32 v[12:13], v[12:13], v[26:27]
	v_pk_add_f32 v[18:19], v[10:11], v[20:21]
	v_pk_add_f32 v[20:21], v[8:9], v[28:29]
	v_cvt_pk_bf16_f32 v8, v12, v13
	v_cvt_pk_bf16_f32 v9, v14, v15
	v_mul_f32_e32 v13, v13, v13
	v_cvt_pk_bf16_f32 v10, v20, v21
	v_cvt_pk_bf16_f32 v11, v18, v19
	global_store_dwordx4 v[22:23], v[8:11], off
	s_nop 0
	v_mul_f32_e32 v14, v14, v14
	s_waitcnt lgkmcnt(0)
	v_mul_f32_e32 v17, v20, v20
	v_fmac_f32_e32 v13, v12, v12
	v_fmac_f32_e32 v14, v15, v15
	v_mul_f32_e32 v18, v18, v18
	v_fmac_f32_e32 v17, v21, v21
	v_add_f32_e32 v12, v13, v14
	v_fmac_f32_e32 v18, v19, v19
	v_add_f32_e32 v12, v17, v12
	v_add_f32_e32 v17, v18, v12
	s_waitcnt vmcnt(15)
	v_mov_b64_e32 v[8:9], v[216:217]
	v_mov_b64_e32 v[10:11], v[218:219]
	v_lshlrev_b32_e32 v12, 16, v8
	v_and_b32_e32 v13, 0xffff0000, v8
	v_lshlrev_b32_e32 v8, 16, v9
	v_and_b32_e32 v9, 0xffff0000, v9
	v_lshlrev_b32_e32 v14, 16, v10
	v_and_b32_e32 v15, 0xffff0000, v10
	v_lshlrev_b32_e32 v10, 16, v11
	v_and_b32_e32 v11, 0xffff0000, v11
	v_pk_add_f32 v[6:7], v[6:7], v[8:9]
	v_pk_add_f32 v[4:5], v[4:5], v[12:13]
	v_pk_add_f32 v[8:9], v[2:3], v[10:11]
	v_pk_add_f32 v[10:11], v[0:1], v[14:15]
	v_mul_f32_e32 v0, v5, v5
	v_mul_f32_e32 v1, v6, v6
	v_mul_f32_e32 v2, v10, v10
	v_fmac_f32_e32 v0, v4, v4
	v_fmac_f32_e32 v1, v7, v7
	v_mul_f32_e32 v3, v8, v8
	v_fmac_f32_e32 v2, v11, v11
	v_add_f32_e32 v0, v0, v1
	v_add_f32_e32 v0, v2, v0
	v_fmac_f32_e32 v3, v9, v9
	v_add_f32_e32 v0, v3, v0
	v_add_f32_e32 v0, v17, v0
	ds_bpermute_b32 v1, v120, v0
	v_cvt_pk_bf16_f32 v2, v4, v5
	v_cvt_pk_bf16_f32 v3, v6, v7
	v_cvt_pk_bf16_f32 v4, v10, v11
	v_cvt_pk_bf16_f32 v5, v8, v9
	s_waitcnt lgkmcnt(0)
	v_add_f32_e32 v0, v0, v1
	ds_bpermute_b32 v1, v112, v0
	global_store_dwordx4 v[22:23], v[2:5], off offset:256
	s_and_saveexec_b64 s[0:1], vcc
	s_cbranch_execz .LBB0_608
	v_lshl_add_u32 v2, v16, 4, s2
	s_waitcnt lgkmcnt(0)
	v_add_f32_e32 v0, v0, v1
	ds_write_b32 v2, v0

.LBB0_671:
	ds_read_b128 v[156:159], v151
	ds_read_b128 v[160:163], v151 offset:1024
	ds_read_b128 v[164:167], v151 offset:2048
	ds_read_b128 v[168:171], v151 offset:3072
	ds_read_b128 v[172:175], v152
	ds_read_b128 v[176:179], v152 offset:1024
	ds_read_b128 v[180:183], v152 offset:2048
	ds_read_b128 v[184:187], v152 offset:3072
	s_add_u32 s28, s26, 0xfff80080
	s_addc_u32 s29, s27, -1
	s_cmp_eq_u32 s53, 28
	s_cselect_b32 s31, s19, s29
	s_cselect_b32 s30, s49, s28
	s_cselect_b32 s29, s17, s52
	s_cselect_b32 s28, s50, s51
	v_lshl_add_u64 v[146:147], s[26:27], 0, v[138:139]
	s_add_i32 m0, s25, 0xc000
	ds_read_b128 v[188:191], v153
	ds_read_b128 v[192:195], v153 offset:1024
	ds_read_b128 v[196:199], v153 offset:2048
	ds_read_b128 v[200:203], v153 offset:3072
	ds_read_b128 v[204:207], v153 offset:4096
	ds_read_b128 v[208:211], v153 offset:5120
	ds_read_b128 v[212:215], v153 offset:6144
	ds_read_b128 v[216:219], v153 offset:7168
	global_load_lds_dwordx4 v[146:147], off
	v_lshl_add_u64 v[146:147], s[26:27], 0, v[140:141]
	s_add_i32 m0, s25, 0xe000
	s_nop 0
	global_load_lds_dwordx4 v[146:147], off
	s_waitcnt vmcnt(8)
	s_waitcnt lgkmcnt(0)
	s_setprio 1
	s_waitcnt lgkmcnt(0)
	v_mfma_f32_16x16x32_bf16 v[116:119], v[156:159], v[188:191], v[116:119]
	v_mfma_f32_16x16x32_bf16 v[112:115], v[164:167], v[188:191], v[112:115]
	v_mfma_f32_16x16x32_bf16 v[100:103], v[156:159], v[196:199], v[100:103]
	v_mfma_f32_16x16x32_bf16 v[96:99], v[164:167], v[196:199], v[96:99]
	s_barrier
	v_mfma_f32_16x16x32_bf16 v[84:87], v[156:159], v[204:207], v[84:87]
	v_mfma_f32_16x16x32_bf16 v[80:83], v[164:167], v[204:207], v[80:83]
	v_mfma_f32_16x16x32_bf16 v[68:71], v[156:159], v[212:215], v[68:71]
	v_mfma_f32_16x16x32_bf16 v[64:67], v[164:167], v[212:215], v[64:67]
	v_mfma_f32_16x16x32_bf16 v[116:119], v[160:163], v[192:195], v[116:119]
	v_mfma_f32_16x16x32_bf16 v[112:115], v[168:171], v[192:195], v[112:115]
	v_mfma_f32_16x16x32_bf16 v[100:103], v[160:163], v[200:203], v[100:103]
	v_mfma_f32_16x16x32_bf16 v[96:99], v[168:171], v[200:203], v[96:99]
	v_mfma_f32_16x16x32_bf16 v[84:87], v[160:163], v[208:211], v[84:87]
	v_mfma_f32_16x16x32_bf16 v[80:83], v[168:171], v[208:211], v[80:83]
	v_mfma_f32_16x16x32_bf16 v[68:71], v[160:163], v[216:219], v[68:71]
	v_mfma_f32_16x16x32_bf16 v[64:67], v[168:171], v[216:219], v[64:67]
	s_setprio 0
	s_setprio 1
	v_mfma_f32_16x16x32_bf16 v[124:127], v[172:175], v[188:191], v[124:127]
	v_mfma_f32_16x16x32_bf16 v[120:123], v[180:183], v[188:191], v[120:123]
	v_mfma_f32_16x16x32_bf16 v[108:111], v[172:175], v[196:199], v[108:111]
	v_mfma_f32_16x16x32_bf16 v[104:107], v[180:183], v[196:199], v[104:107]
	v_mfma_f32_16x16x32_bf16 v[92:95], v[172:175], v[204:207], v[92:95]
	v_mfma_f32_16x16x32_bf16 v[88:91], v[180:183], v[204:207], v[88:91]
	v_mfma_f32_16x16x32_bf16 v[76:79], v[172:175], v[212:215], v[76:79]
	v_mfma_f32_16x16x32_bf16 v[72:75], v[180:183], v[212:215], v[72:75]
	v_mfma_f32_16x16x32_bf16 v[124:127], v[176:179], v[192:195], v[124:127]
	v_mfma_f32_16x16x32_bf16 v[120:123], v[184:187], v[192:195], v[120:123]
	v_mfma_f32_16x16x32_bf16 v[108:111], v[176:179], v[200:203], v[108:111]
	v_mfma_f32_16x16x32_bf16 v[104:107], v[184:187], v[200:203], v[104:107]
	v_mfma_f32_16x16x32_bf16 v[92:95], v[176:179], v[208:211], v[92:95]
	v_mfma_f32_16x16x32_bf16 v[88:91], v[184:187], v[208:211], v[88:91]
	v_mfma_f32_16x16x32_bf16 v[76:79], v[176:179], v[216:219], v[76:79]
	v_mfma_f32_16x16x32_bf16 v[72:75], v[184:187], v[216:219], v[72:75]
	s_setprio 0
	s_barrier
	s_add_i32 s54, s46, s36
	v_lshl_add_u64 v[146:147], s[28:29], 0, v[134:135]
	s_mov_b32 m0, s54
	ds_read_b128 v[188:191], v153 offset:16384
	ds_read_b128 v[192:195], v153 offset:17408
	ds_read_b128 v[196:199], v153 offset:18432
	ds_read_b128 v[200:203], v153 offset:19456
	ds_read_b128 v[204:207], v153 offset:20480
	ds_read_b128 v[208:211], v153 offset:21504
	ds_read_b128 v[212:215], v153 offset:22528
	ds_read_b128 v[216:219], v153 offset:23552
	global_load_lds_dwordx4 v[146:147], off
	s_add_i32 m0, s54, 0x2000
	s_add_u32 s54, s28, 0x80000
	v_lshl_add_u64 v[220:221], s[28:29], 0, v[130:131]
	s_addc_u32 s55, s29, 0
	s_add_i32 s56, s47, s36
	global_load_lds_dwordx4 v[220:221], off
	v_lshl_add_u64 v[222:223], s[54:55], 0, v[134:135]
	s_mov_b32 m0, s56
	v_lshl_add_u64 v[224:225], s[30:31], 0, v[132:133]
	global_load_lds_dwordx4 v[222:223], off
	v_lshl_add_u64 v[222:223], s[54:55], 0, v[130:131]
	s_add_i32 m0, s56, 0x2000
	s_nop 0
	global_load_lds_dwordx4 v[222:223], off
	v_lshl_add_u64 v[222:223], s[30:31], 0, v[136:137]
	s_mov_b32 m0, s25
	s_nop 0
	global_load_lds_dwordx4 v[222:223], off
	s_mov_b32 m0, s39
	s_nop 0
	global_load_lds_dwordx4 v[224:225], off
	s_waitcnt vmcnt(8)
	s_waitcnt lgkmcnt(0)
	s_setprio 1
	s_waitcnt lgkmcnt(0)
	v_mfma_f32_16x16x32_bf16 v[52:55], v[156:159], v[188:191], v[52:55]
	v_mfma_f32_16x16x32_bf16 v[48:51], v[164:167], v[188:191], v[48:51]
	v_mfma_f32_16x16x32_bf16 v[36:39], v[156:159], v[196:199], v[36:39]
	v_mfma_f32_16x16x32_bf16 v[32:35], v[164:167], v[196:199], v[32:35]
	s_barrier
	v_mfma_f32_16x16x32_bf16 v[20:23], v[156:159], v[204:207], v[20:23]
	v_mfma_f32_16x16x32_bf16 v[16:19], v[164:167], v[204:207], v[16:19]
	v_mfma_f32_16x16x32_bf16 v[8:11], v[156:159], v[212:215], v[8:11]
	v_mfma_f32_16x16x32_bf16 v[0:3], v[164:167], v[212:215], v[0:3]
	v_mfma_f32_16x16x32_bf16 v[52:55], v[160:163], v[192:195], v[52:55]
	v_mfma_f32_16x16x32_bf16 v[48:51], v[168:171], v[192:195], v[48:51]
	v_mfma_f32_16x16x32_bf16 v[36:39], v[160:163], v[200:203], v[36:39]
	v_mfma_f32_16x16x32_bf16 v[32:35], v[168:171], v[200:203], v[32:35]
	v_mfma_f32_16x16x32_bf16 v[20:23], v[160:163], v[208:211], v[20:23]
	v_mfma_f32_16x16x32_bf16 v[16:19], v[168:171], v[208:211], v[16:19]
	v_mfma_f32_16x16x32_bf16 v[8:11], v[160:163], v[216:219], v[8:11]
	v_mfma_f32_16x16x32_bf16 v[0:3], v[168:171], v[216:219], v[0:3]
	s_setprio 0
	s_setprio 1
	v_mfma_f32_16x16x32_bf16 v[60:63], v[172:175], v[188:191], v[60:63]
	v_mfma_f32_16x16x32_bf16 v[56:59], v[180:183], v[188:191], v[56:59]
	v_mfma_f32_16x16x32_bf16 v[44:47], v[172:175], v[196:199], v[44:47]
	v_mfma_f32_16x16x32_bf16 v[40:43], v[180:183], v[196:199], v[40:43]
	v_mfma_f32_16x16x32_bf16 v[28:31], v[172:175], v[204:207], v[28:31]
	v_mfma_f32_16x16x32_bf16 v[24:27], v[180:183], v[204:207], v[24:27]
	v_mfma_f32_16x16x32_bf16 v[12:15], v[172:175], v[212:215], v[12:15]
	v_mfma_f32_16x16x32_bf16 v[4:7], v[180:183], v[212:215], v[4:7]
	v_mfma_f32_16x16x32_bf16 v[60:63], v[176:179], v[192:195], v[60:63]
	v_mfma_f32_16x16x32_bf16 v[56:59], v[184:187], v[192:195], v[56:59]
	v_mfma_f32_16x16x32_bf16 v[44:47], v[176:179], v[200:203], v[44:47]
	v_mfma_f32_16x16x32_bf16 v[40:43], v[184:187], v[200:203], v[40:43]
	v_mfma_f32_16x16x32_bf16 v[28:31], v[176:179], v[208:211], v[28:31]
	v_mfma_f32_16x16x32_bf16 v[24:27], v[184:187], v[208:211], v[24:27]
	v_mfma_f32_16x16x32_bf16 v[12:15], v[176:179], v[216:219], v[12:15]
	v_mfma_f32_16x16x32_bf16 v[4:7], v[184:187], v[216:219], v[4:7]
	s_setprio 0
	s_barrier
	s_add_i32 s54, 0, 0x18000
	v_add_u32_e32 v155, s54, v149
	s_add_i32 s55, 0, 0x1c000
	ds_read_b128 v[156:159], v155
	ds_read_b128 v[160:163], v155 offset:1024
	ds_read_b128 v[164:167], v155 offset:2048
	ds_read_b128 v[168:171], v155 offset:3072
	v_add_u32_e32 v155, s55, v149
	ds_read_b128 v[172:175], v155
	ds_read_b128 v[176:179], v155 offset:1024
	ds_read_b128 v[180:183], v155 offset:2048
	ds_read_b128 v[184:187], v155 offset:3072
	s_add_u32 s30, s30, 0x80000
	s_addc_u32 s31, s31, 0
	s_mov_b32 m0, s40
	v_lshl_add_u64 v[226:227], s[30:31], 0, v[136:137]
	ds_read_b128 v[188:191], v153 offset:32768
	ds_read_b128 v[192:195], v153 offset:33792
	ds_read_b128 v[196:199], v153 offset:34816
	ds_read_b128 v[200:203], v153 offset:35840
	ds_read_b128 v[204:207], v153 offset:36864
	ds_read_b128 v[208:211], v153 offset:37888
	ds_read_b128 v[212:215], v153 offset:38912
	ds_read_b128 v[216:219], v153 offset:39936
	global_load_lds_dwordx4 v[226:227], off
	v_lshl_add_u64 v[226:227], s[30:31], 0, v[132:133]
	s_mov_b32 m0, s41
	s_nop 0
	global_load_lds_dwordx4 v[226:227], off
	s_waitcnt vmcnt(8)
	s_waitcnt lgkmcnt(0)
	s_setprio 1
	s_waitcnt lgkmcnt(0)
	v_mfma_f32_16x16x32_bf16 v[116:119], v[156:159], v[188:191], v[116:119]
	v_mfma_f32_16x16x32_bf16 v[112:115], v[164:167], v[188:191], v[112:115]
	v_mfma_f32_16x16x32_bf16 v[100:103], v[156:159], v[196:199], v[100:103]
	v_mfma_f32_16x16x32_bf16 v[96:99], v[164:167], v[196:199], v[96:99]
	s_barrier
	v_mfma_f32_16x16x32_bf16 v[84:87], v[156:159], v[204:207], v[84:87]
	v_mfma_f32_16x16x32_bf16 v[80:83], v[164:167], v[204:207], v[80:83]
	v_mfma_f32_16x16x32_bf16 v[68:71], v[156:159], v[212:215], v[68:71]
	v_mfma_f32_16x16x32_bf16 v[64:67], v[164:167], v[212:215], v[64:67]
	v_mfma_f32_16x16x32_bf16 v[116:119], v[160:163], v[192:195], v[116:119]
	v_mfma_f32_16x16x32_bf16 v[112:115], v[168:171], v[192:195], v[112:115]
	v_mfma_f32_16x16x32_bf16 v[100:103], v[160:163], v[200:203], v[100:103]
	v_mfma_f32_16x16x32_bf16 v[96:99], v[168:171], v[200:203], v[96:99]
	v_mfma_f32_16x16x32_bf16 v[84:87], v[160:163], v[208:211], v[84:87]
	v_mfma_f32_16x16x32_bf16 v[80:83], v[168:171], v[208:211], v[80:83]
	v_mfma_f32_16x16x32_bf16 v[68:71], v[160:163], v[216:219], v[68:71]
	v_mfma_f32_16x16x32_bf16 v[64:67], v[168:171], v[216:219], v[64:67]
	s_setprio 0
	s_setprio 1
	v_mfma_f32_16x16x32_bf16 v[124:127], v[172:175], v[188:191], v[124:127]
	v_mfma_f32_16x16x32_bf16 v[120:123], v[180:183], v[188:191], v[120:123]
	v_mfma_f32_16x16x32_bf16 v[108:111], v[172:175], v[196:199], v[108:111]
	v_mfma_f32_16x16x32_bf16 v[104:107], v[180:183], v[196:199], v[104:107]
	v_mfma_f32_16x16x32_bf16 v[92:95], v[172:175], v[204:207], v[92:95]
	v_mfma_f32_16x16x32_bf16 v[88:91], v[180:183], v[204:207], v[88:91]
	v_mfma_f32_16x16x32_bf16 v[76:79], v[172:175], v[212:215], v[76:79]
	v_mfma_f32_16x16x32_bf16 v[72:75], v[180:183], v[212:215], v[72:75]
	v_mfma_f32_16x16x32_bf16 v[124:127], v[176:179], v[192:195], v[124:127]
	v_mfma_f32_16x16x32_bf16 v[120:123], v[184:187], v[192:195], v[120:123]
	v_mfma_f32_16x16x32_bf16 v[108:111], v[176:179], v[200:203], v[108:111]
	v_mfma_f32_16x16x32_bf16 v[104:107], v[184:187], v[200:203], v[104:107]
	v_mfma_f32_16x16x32_bf16 v[92:95], v[176:179], v[208:211], v[92:95]
	v_mfma_f32_16x16x32_bf16 v[88:91], v[184:187], v[208:211], v[88:91]
	v_mfma_f32_16x16x32_bf16 v[76:79], v[176:179], v[216:219], v[76:79]
	v_mfma_f32_16x16x32_bf16 v[72:75], v[184:187], v[216:219], v[72:75]
	s_setprio 0
	s_barrier
	s_add_i32 s30, s54, s36
	v_lshl_add_u64 v[146:147], v[146:147], 0, s[12:13]
	s_mov_b32 m0, s30
	ds_read_b128 v[188:191], v153 offset:49152
	ds_read_b128 v[192:195], v153 offset:50176
	ds_read_b128 v[196:199], v153 offset:51200
	ds_read_b128 v[200:203], v153 offset:52224
	ds_read_b128 v[204:207], v153 offset:53248
	ds_read_b128 v[208:211], v153 offset:54272
	ds_read_b128 v[212:215], v153 offset:55296
	ds_read_b128 v[216:219], v153 offset:56320
	global_load_lds_dwordx4 v[146:147], off
	s_add_i32 m0, s30, 0x2000
	s_add_u32 s28, s28, 0x80080
	v_lshl_add_u64 v[146:147], v[220:221], 0, s[12:13]
	s_addc_u32 s29, s29, 0
	s_add_i32 s30, s55, s36
	global_load_lds_dwordx4 v[146:147], off
	v_lshl_add_u64 v[146:147], s[28:29], 0, v[134:135]
	s_mov_b32 m0, s30
	s_nop 0
	global_load_lds_dwordx4 v[146:147], off
	v_lshl_add_u64 v[146:147], s[28:29], 0, v[130:131]
	s_add_i32 m0, s30, 0x2000
	s_nop 0
	global_load_lds_dwordx4 v[146:147], off
	v_lshl_add_u64 v[146:147], v[222:223], 0, s[12:13]
	s_mov_b32 m0, s43
	s_nop 0
	global_load_lds_dwordx4 v[146:147], off
	v_lshl_add_u64 v[146:147], v[224:225], 0, s[12:13]
	s_mov_b32 m0, s44
	s_nop 0
	global_load_lds_dwordx4 v[146:147], off
	s_waitcnt vmcnt(8)
	s_waitcnt lgkmcnt(0)
	s_setprio 1
	s_waitcnt lgkmcnt(0)
	v_mfma_f32_16x16x32_bf16 v[52:55], v[156:159], v[188:191], v[52:55]
	v_mfma_f32_16x16x32_bf16 v[48:51], v[164:167], v[188:191], v[48:51]
	v_mfma_f32_16x16x32_bf16 v[36:39], v[156:159], v[196:199], v[36:39]
	v_mfma_f32_16x16x32_bf16 v[32:35], v[164:167], v[196:199], v[32:35]
	s_barrier
	v_mfma_f32_16x16x32_bf16 v[20:23], v[156:159], v[204:207], v[20:23]
	v_mfma_f32_16x16x32_bf16 v[16:19], v[164:167], v[204:207], v[16:19]
	v_mfma_f32_16x16x32_bf16 v[8:11], v[156:159], v[212:215], v[8:11]
	v_mfma_f32_16x16x32_bf16 v[0:3], v[164:167], v[212:215], v[0:3]
	v_mfma_f32_16x16x32_bf16 v[52:55], v[160:163], v[192:195], v[52:55]
	v_mfma_f32_16x16x32_bf16 v[48:51], v[168:171], v[192:195], v[48:51]
	v_mfma_f32_16x16x32_bf16 v[36:39], v[160:163], v[200:203], v[36:39]
	v_mfma_f32_16x16x32_bf16 v[32:35], v[168:171], v[200:203], v[32:35]
	v_mfma_f32_16x16x32_bf16 v[20:23], v[160:163], v[208:211], v[20:23]
	v_mfma_f32_16x16x32_bf16 v[16:19], v[168:171], v[208:211], v[16:19]
	v_mfma_f32_16x16x32_bf16 v[8:11], v[160:163], v[216:219], v[8:11]
	v_mfma_f32_16x16x32_bf16 v[0:3], v[168:171], v[216:219], v[0:3]
	s_setprio 0
	s_setprio 1
	v_mfma_f32_16x16x32_bf16 v[60:63], v[172:175], v[188:191], v[60:63]
	v_mfma_f32_16x16x32_bf16 v[56:59], v[180:183], v[188:191], v[56:59]
	v_mfma_f32_16x16x32_bf16 v[44:47], v[172:175], v[196:199], v[44:47]
	v_mfma_f32_16x16x32_bf16 v[40:43], v[180:183], v[196:199], v[40:43]
	v_mfma_f32_16x16x32_bf16 v[28:31], v[172:175], v[204:207], v[28:31]
	v_mfma_f32_16x16x32_bf16 v[24:27], v[180:183], v[204:207], v[24:27]
	v_mfma_f32_16x16x32_bf16 v[12:15], v[172:175], v[212:215], v[12:15]
	v_mfma_f32_16x16x32_bf16 v[4:7], v[180:183], v[212:215], v[4:7]
	v_mfma_f32_16x16x32_bf16 v[60:63], v[176:179], v[192:195], v[60:63]
	v_mfma_f32_16x16x32_bf16 v[56:59], v[184:187], v[192:195], v[56:59]
	v_mfma_f32_16x16x32_bf16 v[44:47], v[176:179], v[200:203], v[44:47]
	v_mfma_f32_16x16x32_bf16 v[40:43], v[184:187], v[200:203], v[40:43]
	v_mfma_f32_16x16x32_bf16 v[28:31], v[176:179], v[208:211], v[28:31]
	v_mfma_f32_16x16x32_bf16 v[24:27], v[184:187], v[208:211], v[24:27]
	v_mfma_f32_16x16x32_bf16 v[12:15], v[176:179], v[216:219], v[12:15]
	v_mfma_f32_16x16x32_bf16 v[4:7], v[184:187], v[216:219], v[4:7]
	s_setprio 0
	s_barrier
	s_add_i32 s53, s53, 2
	s_add_u32 s26, s26, 0x100
	s_addc_u32 s27, s27, 0
	s_add_u32 s51, s51, 0x100
	s_addc_u32 s52, s52, 0
	s_cmp_gt_u32 s53, 29
	s_cbranch_scc0 .LBB0_671
	s_and_b64 vcc, exec, s[14:15]
	s_cbranch_vccz .LBB0_674
	s_barrier

.LBB0_849:
	v_add_u32_e32 v164, s40, v129
	v_add_u32_e32 v173, s41, v129
	s_add_u32 s22, s14, s20
	ds_read_b128 v[152:155], v164
	ds_read_b128 v[156:159], v164 offset:1024
	ds_read_b128 v[160:163], v164 offset:2048
	ds_read_b128 v[164:167], v164 offset:3072
	ds_read_b128 v[168:171], v173
	ds_read_b128 v[174:177], v173 offset:1024
	ds_read_b128 v[178:181], v173 offset:2048
	ds_read_b128 v[182:185], v173 offset:3072
	s_addc_u32 s23, s15, s21
	s_add_u32 s22, s22, 0x100
	s_addc_u32 s23, s23, 0
	s_add_u32 s48, s45, s20
	s_addc_u32 s49, s46, s21
	s_cmpk_eq_i32 s20, 0x2b00
	s_cselect_b32 s25, s19, s23
	s_cselect_b32 s24, s18, s22
	s_cselect_b32 s23, s7, s49
	s_cselect_b32 s22, s6, s48
	v_lshl_add_u64 v[218:219], v[146:147], 0, s[20:21]
	s_add_i32 m0, s33, 0xc000
	ds_read_b128 v[186:189], v151
	ds_read_b128 v[190:193], v151 offset:1024
	ds_read_b128 v[194:197], v151 offset:2048
	ds_read_b128 v[198:201], v151 offset:3072
	ds_read_b128 v[202:205], v151 offset:4096
	ds_read_b128 v[206:209], v151 offset:5120
	ds_read_b128 v[210:213], v151 offset:6144
	ds_read_b128 v[214:217], v151 offset:7168
	global_load_lds_dwordx4 v[218:219], off
	v_lshl_add_u64 v[218:219], v[148:149], 0, s[20:21]
	s_add_i32 m0, s33, 0xe000
	s_nop 0
	global_load_lds_dwordx4 v[218:219], off
	s_waitcnt vmcnt(8)
	s_waitcnt lgkmcnt(0)
	s_setprio 1
	s_waitcnt lgkmcnt(0)
	v_mfma_f32_16x16x32_bf16 v[124:127], v[152:155], v[186:189], v[124:127]
	v_mfma_f32_16x16x32_bf16 v[120:123], v[160:163], v[186:189], v[120:123]
	v_mfma_f32_16x16x32_bf16 v[108:111], v[152:155], v[194:197], v[108:111]
	v_mfma_f32_16x16x32_bf16 v[104:107], v[160:163], v[194:197], v[104:107]
	s_barrier
	v_mfma_f32_16x16x32_bf16 v[92:95], v[152:155], v[202:205], v[92:95]
	v_mfma_f32_16x16x32_bf16 v[88:91], v[160:163], v[202:205], v[88:91]
	v_mfma_f32_16x16x32_bf16 v[76:79], v[152:155], v[210:213], v[76:79]
	v_mfma_f32_16x16x32_bf16 v[72:75], v[160:163], v[210:213], v[72:75]
	v_mfma_f32_16x16x32_bf16 v[124:127], v[156:159], v[190:193], v[124:127]
	v_mfma_f32_16x16x32_bf16 v[120:123], v[164:167], v[190:193], v[120:123]
	v_mfma_f32_16x16x32_bf16 v[108:111], v[156:159], v[198:201], v[108:111]
	v_mfma_f32_16x16x32_bf16 v[104:107], v[164:167], v[198:201], v[104:107]
	v_mfma_f32_16x16x32_bf16 v[92:95], v[156:159], v[206:209], v[92:95]
	v_mfma_f32_16x16x32_bf16 v[88:91], v[164:167], v[206:209], v[88:91]
	v_mfma_f32_16x16x32_bf16 v[76:79], v[156:159], v[214:217], v[76:79]
	v_mfma_f32_16x16x32_bf16 v[72:75], v[164:167], v[214:217], v[72:75]
	s_setprio 0
	s_setprio 1
	v_mfma_f32_16x16x32_bf16 v[116:119], v[168:171], v[186:189], v[116:119]
	v_mfma_f32_16x16x32_bf16 v[112:115], v[178:181], v[186:189], v[112:115]
	v_mfma_f32_16x16x32_bf16 v[100:103], v[168:171], v[194:197], v[100:103]
	v_mfma_f32_16x16x32_bf16 v[96:99], v[178:181], v[194:197], v[96:99]
	v_mfma_f32_16x16x32_bf16 v[84:87], v[168:171], v[202:205], v[84:87]
	v_mfma_f32_16x16x32_bf16 v[80:83], v[178:181], v[202:205], v[80:83]
	v_mfma_f32_16x16x32_bf16 v[68:71], v[168:171], v[210:213], v[68:71]
	v_mfma_f32_16x16x32_bf16 v[64:67], v[178:181], v[210:213], v[64:67]
	v_mfma_f32_16x16x32_bf16 v[116:119], v[174:177], v[190:193], v[116:119]
	v_mfma_f32_16x16x32_bf16 v[112:115], v[182:185], v[190:193], v[112:115]
	v_mfma_f32_16x16x32_bf16 v[100:103], v[174:177], v[198:201], v[100:103]
	v_mfma_f32_16x16x32_bf16 v[96:99], v[182:185], v[198:201], v[96:99]
	v_mfma_f32_16x16x32_bf16 v[84:87], v[174:177], v[206:209], v[84:87]
	v_mfma_f32_16x16x32_bf16 v[80:83], v[182:185], v[206:209], v[80:83]
	v_mfma_f32_16x16x32_bf16 v[68:71], v[174:177], v[214:217], v[68:71]
	v_mfma_f32_16x16x32_bf16 v[64:67], v[182:185], v[214:217], v[64:67]
	s_setprio 0
	s_barrier
	s_add_i32 s48, s40, s31
	v_lshl_add_u64 v[218:219], s[22:23], 0, v[132:133]
	s_mov_b32 m0, s48
	ds_read_b128 v[186:189], v151 offset:16384
	ds_read_b128 v[190:193], v151 offset:17408
	ds_read_b128 v[194:197], v151 offset:18432
	ds_read_b128 v[198:201], v151 offset:19456
	ds_read_b128 v[202:205], v151 offset:20480
	ds_read_b128 v[206:209], v151 offset:21504
	ds_read_b128 v[210:213], v151 offset:22528
	ds_read_b128 v[214:217], v151 offset:23552
	global_load_lds_dwordx4 v[218:219], off
	s_add_i32 m0, s48, 0x2000
	s_add_u32 s48, s22, 0x160000
	v_lshl_add_u64 v[220:221], s[22:23], 0, v[136:137]
	s_addc_u32 s49, s23, 0
	s_add_i32 s50, s41, s31
	global_load_lds_dwordx4 v[220:221], off
	v_lshl_add_u64 v[222:223], s[48:49], 0, v[132:133]
	s_mov_b32 m0, s50
	v_lshl_add_u64 v[224:225], s[24:25], 0, v[134:135]
	global_load_lds_dwordx4 v[222:223], off
	v_lshl_add_u64 v[222:223], s[48:49], 0, v[136:137]
	s_add_i32 m0, s50, 0x2000
	s_nop 0
	global_load_lds_dwordx4 v[222:223], off
	v_lshl_add_u64 v[222:223], s[24:25], 0, v[130:131]
	s_mov_b32 m0, s33
	s_nop 0
	global_load_lds_dwordx4 v[222:223], off
	s_mov_b32 m0, s34
	s_nop 0
	global_load_lds_dwordx4 v[224:225], off
	s_waitcnt vmcnt(8)
	s_waitcnt lgkmcnt(0)
	s_setprio 1
	s_waitcnt lgkmcnt(0)
	v_mfma_f32_16x16x32_bf16 v[60:63], v[152:155], v[186:189], v[60:63]
	v_mfma_f32_16x16x32_bf16 v[56:59], v[160:163], v[186:189], v[56:59]
	v_mfma_f32_16x16x32_bf16 v[44:47], v[152:155], v[194:197], v[44:47]
	v_mfma_f32_16x16x32_bf16 v[40:43], v[160:163], v[194:197], v[40:43]
	s_barrier
	v_mfma_f32_16x16x32_bf16 v[28:31], v[152:155], v[202:205], v[28:31]
	v_mfma_f32_16x16x32_bf16 v[24:27], v[160:163], v[202:205], v[24:27]
	v_mfma_f32_16x16x32_bf16 v[12:15], v[152:155], v[210:213], v[12:15]
	v_mfma_f32_16x16x32_bf16 v[8:11], v[160:163], v[210:213], v[8:11]
	v_mfma_f32_16x16x32_bf16 v[60:63], v[156:159], v[190:193], v[60:63]
	v_mfma_f32_16x16x32_bf16 v[56:59], v[164:167], v[190:193], v[56:59]
	v_mfma_f32_16x16x32_bf16 v[44:47], v[156:159], v[198:201], v[44:47]
	v_mfma_f32_16x16x32_bf16 v[40:43], v[164:167], v[198:201], v[40:43]
	v_mfma_f32_16x16x32_bf16 v[28:31], v[156:159], v[206:209], v[28:31]
	v_mfma_f32_16x16x32_bf16 v[24:27], v[164:167], v[206:209], v[24:27]
	v_mfma_f32_16x16x32_bf16 v[12:15], v[156:159], v[214:217], v[12:15]
	v_mfma_f32_16x16x32_bf16 v[8:11], v[164:167], v[214:217], v[8:11]
	s_setprio 0
	s_setprio 1
	v_mfma_f32_16x16x32_bf16 v[52:55], v[168:171], v[186:189], v[52:55]
	v_mfma_f32_16x16x32_bf16 v[48:51], v[178:181], v[186:189], v[48:51]
	v_mfma_f32_16x16x32_bf16 v[36:39], v[168:171], v[194:197], v[36:39]
	v_mfma_f32_16x16x32_bf16 v[32:35], v[178:181], v[194:197], v[32:35]
	v_mfma_f32_16x16x32_bf16 v[20:23], v[168:171], v[202:205], v[20:23]
	v_mfma_f32_16x16x32_bf16 v[16:19], v[178:181], v[202:205], v[16:19]
	v_mfma_f32_16x16x32_bf16 v[4:7], v[168:171], v[210:213], v[4:7]
	v_mfma_f32_16x16x32_bf16 v[0:3], v[178:181], v[210:213], v[0:3]
	v_mfma_f32_16x16x32_bf16 v[52:55], v[174:177], v[190:193], v[52:55]
	v_mfma_f32_16x16x32_bf16 v[48:51], v[182:185], v[190:193], v[48:51]
	v_mfma_f32_16x16x32_bf16 v[36:39], v[174:177], v[198:201], v[36:39]
	v_mfma_f32_16x16x32_bf16 v[32:35], v[182:185], v[198:201], v[32:35]
	v_mfma_f32_16x16x32_bf16 v[20:23], v[174:177], v[206:209], v[20:23]
	v_mfma_f32_16x16x32_bf16 v[16:19], v[182:185], v[206:209], v[16:19]
	v_mfma_f32_16x16x32_bf16 v[4:7], v[174:177], v[214:217], v[4:7]
	v_mfma_f32_16x16x32_bf16 v[0:3], v[182:185], v[214:217], v[0:3]
	s_setprio 0
	s_barrier
	s_add_i32 s48, 0, 0x18000
	s_add_i32 s49, 0, 0x1c000
	v_add_u32_e32 v164, s48, v129
	v_add_u32_e32 v173, s49, v129
	ds_read_b128 v[152:155], v164
	ds_read_b128 v[156:159], v164 offset:1024
	ds_read_b128 v[160:163], v164 offset:2048
	ds_read_b128 v[164:167], v164 offset:3072
	ds_read_b128 v[168:171], v173
	ds_read_b128 v[174:177], v173 offset:1024
	ds_read_b128 v[178:181], v173 offset:2048
	ds_read_b128 v[182:185], v173 offset:3072
	s_add_u32 s24, s24, 0x160000
	s_addc_u32 s25, s25, 0
	s_mov_b32 m0, s35
	v_lshl_add_u64 v[226:227], s[24:25], 0, v[130:131]
	ds_read_b128 v[186:189], v151 offset:32768
	ds_read_b128 v[190:193], v151 offset:33792
	ds_read_b128 v[194:197], v151 offset:34816
	ds_read_b128 v[198:201], v151 offset:35840
	ds_read_b128 v[202:205], v151 offset:36864
	ds_read_b128 v[206:209], v151 offset:37888
	ds_read_b128 v[210:213], v151 offset:38912
	ds_read_b128 v[214:217], v151 offset:39936
	global_load_lds_dwordx4 v[226:227], off
	v_lshl_add_u64 v[226:227], s[24:25], 0, v[134:135]
	s_mov_b32 m0, s36
	s_nop 0
	global_load_lds_dwordx4 v[226:227], off
	s_waitcnt vmcnt(8)
	s_waitcnt lgkmcnt(0)
	s_setprio 1
	s_waitcnt lgkmcnt(0)
	v_mfma_f32_16x16x32_bf16 v[124:127], v[152:155], v[186:189], v[124:127]
	v_mfma_f32_16x16x32_bf16 v[120:123], v[160:163], v[186:189], v[120:123]
	v_mfma_f32_16x16x32_bf16 v[108:111], v[152:155], v[194:197], v[108:111]
	v_mfma_f32_16x16x32_bf16 v[104:107], v[160:163], v[194:197], v[104:107]
	s_barrier
	v_mfma_f32_16x16x32_bf16 v[92:95], v[152:155], v[202:205], v[92:95]
	v_mfma_f32_16x16x32_bf16 v[88:91], v[160:163], v[202:205], v[88:91]
	v_mfma_f32_16x16x32_bf16 v[76:79], v[152:155], v[210:213], v[76:79]
	v_mfma_f32_16x16x32_bf16 v[72:75], v[160:163], v[210:213], v[72:75]
	v_mfma_f32_16x16x32_bf16 v[124:127], v[156:159], v[190:193], v[124:127]
	v_mfma_f32_16x16x32_bf16 v[120:123], v[164:167], v[190:193], v[120:123]
	v_mfma_f32_16x16x32_bf16 v[108:111], v[156:159], v[198:201], v[108:111]
	v_mfma_f32_16x16x32_bf16 v[104:107], v[164:167], v[198:201], v[104:107]
	v_mfma_f32_16x16x32_bf16 v[92:95], v[156:159], v[206:209], v[92:95]
	v_mfma_f32_16x16x32_bf16 v[88:91], v[164:167], v[206:209], v[88:91]
	v_mfma_f32_16x16x32_bf16 v[76:79], v[156:159], v[214:217], v[76:79]
	v_mfma_f32_16x16x32_bf16 v[72:75], v[164:167], v[214:217], v[72:75]
	s_setprio 0
	s_setprio 1
	v_mfma_f32_16x16x32_bf16 v[116:119], v[168:171], v[186:189], v[116:119]
	v_mfma_f32_16x16x32_bf16 v[112:115], v[178:181], v[186:189], v[112:115]
	v_mfma_f32_16x16x32_bf16 v[100:103], v[168:171], v[194:197], v[100:103]
	v_mfma_f32_16x16x32_bf16 v[96:99], v[178:181], v[194:197], v[96:99]
	v_mfma_f32_16x16x32_bf16 v[84:87], v[168:171], v[202:205], v[84:87]
	v_mfma_f32_16x16x32_bf16 v[80:83], v[178:181], v[202:205], v[80:83]
	v_mfma_f32_16x16x32_bf16 v[68:71], v[168:171], v[210:213], v[68:71]
	v_mfma_f32_16x16x32_bf16 v[64:67], v[178:181], v[210:213], v[64:67]
	v_mfma_f32_16x16x32_bf16 v[116:119], v[174:177], v[190:193], v[116:119]
	v_mfma_f32_16x16x32_bf16 v[112:115], v[182:185], v[190:193], v[112:115]
	v_mfma_f32_16x16x32_bf16 v[100:103], v[174:177], v[198:201], v[100:103]
	v_mfma_f32_16x16x32_bf16 v[96:99], v[182:185], v[198:201], v[96:99]
	v_mfma_f32_16x16x32_bf16 v[84:87], v[174:177], v[206:209], v[84:87]
	v_mfma_f32_16x16x32_bf16 v[80:83], v[182:185], v[206:209], v[80:83]
	v_mfma_f32_16x16x32_bf16 v[68:71], v[174:177], v[214:217], v[68:71]
	v_mfma_f32_16x16x32_bf16 v[64:67], v[182:185], v[214:217], v[64:67]
	s_setprio 0
	s_barrier
	s_add_i32 s24, s48, s31
	v_lshl_add_u64 v[218:219], v[218:219], 0, s[16:17]
	s_mov_b32 m0, s24
	ds_read_b128 v[186:189], v151 offset:49152
	ds_read_b128 v[190:193], v151 offset:50176
	ds_read_b128 v[194:197], v151 offset:51200
	ds_read_b128 v[198:201], v151 offset:52224
	ds_read_b128 v[202:205], v151 offset:53248
	ds_read_b128 v[206:209], v151 offset:54272
	ds_read_b128 v[210:213], v151 offset:55296
	ds_read_b128 v[214:217], v151 offset:56320
	global_load_lds_dwordx4 v[218:219], off
	s_add_i32 m0, s24, 0x2000
	s_add_u32 s22, s22, 0x160080
	v_lshl_add_u64 v[218:219], v[220:221], 0, s[16:17]
	s_addc_u32 s23, s23, 0
	s_add_i32 s24, s49, s31
	global_load_lds_dwordx4 v[218:219], off
	v_lshl_add_u64 v[218:219], s[22:23], 0, v[132:133]
	s_mov_b32 m0, s24
	s_nop 0
	global_load_lds_dwordx4 v[218:219], off
	v_lshl_add_u64 v[218:219], s[22:23], 0, v[136:137]
	s_add_i32 m0, s24, 0x2000
	s_nop 0
	global_load_lds_dwordx4 v[218:219], off
	v_lshl_add_u64 v[218:219], v[222:223], 0, s[16:17]
	s_mov_b32 m0, s37
	s_nop 0
	global_load_lds_dwordx4 v[218:219], off
	v_lshl_add_u64 v[218:219], v[224:225], 0, s[16:17]
	s_mov_b32 m0, s38
	s_nop 0
	global_load_lds_dwordx4 v[218:219], off
	s_waitcnt vmcnt(8)
	s_waitcnt lgkmcnt(0)
	s_setprio 1
	s_waitcnt lgkmcnt(0)
	v_mfma_f32_16x16x32_bf16 v[60:63], v[152:155], v[186:189], v[60:63]
	v_mfma_f32_16x16x32_bf16 v[56:59], v[160:163], v[186:189], v[56:59]
	v_mfma_f32_16x16x32_bf16 v[44:47], v[152:155], v[194:197], v[44:47]
	v_mfma_f32_16x16x32_bf16 v[40:43], v[160:163], v[194:197], v[40:43]
	s_barrier
	v_mfma_f32_16x16x32_bf16 v[28:31], v[152:155], v[202:205], v[28:31]
	v_mfma_f32_16x16x32_bf16 v[24:27], v[160:163], v[202:205], v[24:27]
	v_mfma_f32_16x16x32_bf16 v[12:15], v[152:155], v[210:213], v[12:15]
	v_mfma_f32_16x16x32_bf16 v[8:11], v[160:163], v[210:213], v[8:11]
	v_mfma_f32_16x16x32_bf16 v[60:63], v[156:159], v[190:193], v[60:63]
	v_mfma_f32_16x16x32_bf16 v[56:59], v[164:167], v[190:193], v[56:59]
	v_mfma_f32_16x16x32_bf16 v[44:47], v[156:159], v[198:201], v[44:47]
	v_mfma_f32_16x16x32_bf16 v[40:43], v[164:167], v[198:201], v[40:43]
	v_mfma_f32_16x16x32_bf16 v[28:31], v[156:159], v[206:209], v[28:31]
	v_mfma_f32_16x16x32_bf16 v[24:27], v[164:167], v[206:209], v[24:27]
	v_mfma_f32_16x16x32_bf16 v[12:15], v[156:159], v[214:217], v[12:15]
	v_mfma_f32_16x16x32_bf16 v[8:11], v[164:167], v[214:217], v[8:11]
	s_setprio 0
	s_setprio 1
	v_mfma_f32_16x16x32_bf16 v[52:55], v[168:171], v[186:189], v[52:55]
	v_mfma_f32_16x16x32_bf16 v[48:51], v[178:181], v[186:189], v[48:51]
	v_mfma_f32_16x16x32_bf16 v[36:39], v[168:171], v[194:197], v[36:39]
	v_mfma_f32_16x16x32_bf16 v[32:35], v[178:181], v[194:197], v[32:35]
	v_mfma_f32_16x16x32_bf16 v[20:23], v[168:171], v[202:205], v[20:23]
	v_mfma_f32_16x16x32_bf16 v[16:19], v[178:181], v[202:205], v[16:19]
	v_mfma_f32_16x16x32_bf16 v[4:7], v[168:171], v[210:213], v[4:7]
	v_mfma_f32_16x16x32_bf16 v[0:3], v[178:181], v[210:213], v[0:3]
	v_mfma_f32_16x16x32_bf16 v[52:55], v[174:177], v[190:193], v[52:55]
	v_mfma_f32_16x16x32_bf16 v[48:51], v[182:185], v[190:193], v[48:51]
	v_mfma_f32_16x16x32_bf16 v[36:39], v[174:177], v[198:201], v[36:39]
	v_mfma_f32_16x16x32_bf16 v[32:35], v[182:185], v[198:201], v[32:35]
	v_mfma_f32_16x16x32_bf16 v[20:23], v[174:177], v[206:209], v[20:23]
	v_mfma_f32_16x16x32_bf16 v[16:19], v[182:185], v[206:209], v[16:19]
	v_mfma_f32_16x16x32_bf16 v[4:7], v[174:177], v[214:217], v[4:7]
	v_mfma_f32_16x16x32_bf16 v[0:3], v[182:185], v[214:217], v[0:3]
	s_setprio 0
	s_barrier
	s_add_i32 s47, s47, 2
	s_add_u32 s20, s20, 0x100
	s_addc_u32 s21, s21, 0
	s_cmpk_gt_u32 s47, 0x55
	s_cbranch_scc0 .LBB0_849
	s_add_u32 s20, s45, 0xffffff00
	s_addc_u32 s21, s46, -1
	s_and_b64 vcc, exec, s[4:5]
	s_cbranch_vccnz .LBB0_852
	v_mov_b32_e32 v0, 0
	s_mov_b32 s12, s42
	s_mov_b32 s13, s43
	s_mov_b64 s[14:15], s[18:19]
	s_mov_b32 s39, s44
	v_mov_b32_e32 v1, v0
	v_mov_b32_e32 v2, v0
	v_mov_b32_e32 v3, v0
	v_mov_b32_e32 v4, v0
	v_mov_b32_e32 v5, v0
	v_mov_b32_e32 v6, v0
	v_mov_b32_e32 v7, v0
	v_mov_b32_e32 v16, v0
	v_mov_b32_e32 v17, v0
	v_mov_b32_e32 v18, v0
	v_mov_b32_e32 v19, v0
	v_mov_b32_e32 v20, v0
	v_mov_b32_e32 v21, v0
	v_mov_b32_e32 v22, v0
	v_mov_b32_e32 v23, v0
	v_mov_b32_e32 v32, v0
	v_mov_b32_e32 v33, v0
	v_mov_b32_e32 v34, v0
	v_mov_b32_e32 v35, v0
	v_mov_b32_e32 v36, v0
	v_mov_b32_e32 v37, v0
	v_mov_b32_e32 v38, v0
	v_mov_b32_e32 v39, v0
	v_mov_b32_e32 v48, v0
	v_mov_b32_e32 v49, v0
	v_mov_b32_e32 v50, v0
	v_mov_b32_e32 v51, v0
	v_mov_b32_e32 v52, v0
	v_mov_b32_e32 v53, v0
	v_mov_b32_e32 v54, v0
	v_mov_b32_e32 v55, v0
	v_mov_b32_e32 v8, v0
	v_mov_b32_e32 v9, v0
	v_mov_b32_e32 v10, v0
	v_mov_b32_e32 v11, v0
	v_mov_b32_e32 v12, v0
	v_mov_b32_e32 v13, v0
	v_mov_b32_e32 v14, v0
	v_mov_b32_e32 v15, v0
	v_mov_b32_e32 v24, v0
	v_mov_b32_e32 v25, v0
	v_mov_b32_e32 v26, v0
	v_mov_b32_e32 v27, v0
	v_mov_b32_e32 v28, v0
	v_mov_b32_e32 v29, v0
	v_mov_b32_e32 v30, v0
	v_mov_b32_e32 v31, v0
	v_mov_b32_e32 v40, v0
	v_mov_b32_e32 v41, v0
	v_mov_b32_e32 v42, v0
	v_mov_b32_e32 v43, v0
	v_mov_b32_e32 v44, v0
	v_mov_b32_e32 v45, v0
	v_mov_b32_e32 v46, v0
	v_mov_b32_e32 v47, v0
	v_mov_b32_e32 v56, v0
	v_mov_b32_e32 v57, v0
	v_mov_b32_e32 v58, v0
	v_mov_b32_e32 v59, v0
	v_mov_b32_e32 v60, v0
	v_mov_b32_e32 v61, v0
	v_mov_b32_e32 v62, v0
	v_mov_b32_e32 v63, v0
	v_mov_b32_e32 v64, v0
	v_mov_b32_e32 v65, v0
	v_mov_b32_e32 v66, v0
	v_mov_b32_e32 v67, v0
	v_mov_b32_e32 v68, v0
	v_mov_b32_e32 v69, v0
	v_mov_b32_e32 v70, v0
	v_mov_b32_e32 v71, v0
	v_mov_b32_e32 v80, v0
	v_mov_b32_e32 v81, v0
	v_mov_b32_e32 v82, v0
	v_mov_b32_e32 v83, v0
	v_mov_b32_e32 v84, v0
	v_mov_b32_e32 v85, v0
	v_mov_b32_e32 v86, v0
	v_mov_b32_e32 v87, v0
	v_mov_b32_e32 v96, v0
	v_mov_b32_e32 v97, v0
	v_mov_b32_e32 v98, v0
	v_mov_b32_e32 v99, v0
	v_mov_b32_e32 v100, v0
	v_mov_b32_e32 v101, v0
	v_mov_b32_e32 v102, v0
	v_mov_b32_e32 v103, v0
	v_mov_b32_e32 v112, v0
	v_mov_b32_e32 v113, v0
	v_mov_b32_e32 v114, v0
	v_mov_b32_e32 v115, v0
	v_mov_b32_e32 v116, v0
	v_mov_b32_e32 v117, v0
	v_mov_b32_e32 v118, v0
	v_mov_b32_e32 v119, v0
	v_mov_b32_e32 v72, v0
	v_mov_b32_e32 v73, v0
	v_mov_b32_e32 v74, v0
	v_mov_b32_e32 v75, v0
	v_mov_b32_e32 v76, v0
	v_mov_b32_e32 v77, v0
	v_mov_b32_e32 v78, v0
	v_mov_b32_e32 v79, v0
	v_mov_b32_e32 v88, v0
	v_mov_b32_e32 v89, v0
	v_mov_b32_e32 v90, v0
	v_mov_b32_e32 v91, v0
	v_mov_b32_e32 v92, v0
	v_mov_b32_e32 v93, v0
	v_mov_b32_e32 v94, v0
	v_mov_b32_e32 v95, v0
	v_mov_b32_e32 v104, v0
	v_mov_b32_e32 v105, v0
	v_mov_b32_e32 v106, v0
	v_mov_b32_e32 v107, v0
	v_mov_b32_e32 v108, v0
	v_mov_b32_e32 v109, v0
	v_mov_b32_e32 v110, v0
	v_mov_b32_e32 v111, v0
	v_mov_b32_e32 v120, v0
	v_mov_b32_e32 v121, v0
	v_mov_b32_e32 v122, v0
	v_mov_b32_e32 v123, v0
	v_mov_b32_e32 v124, v0
	v_mov_b32_e32 v125, v0
	v_mov_b32_e32 v126, v0
	v_mov_b32_e32 v127, v0
	s_andn2_b64 vcc, exec, s[0:1]
	s_cbranch_vccnz .LBB0_853
	s_branch .LBB0_854
